# v97 + EpiResid epilogues rewritten row-major: both 64B halves of each 128B line loaded and stored back to back (depth-4 pipeline, all gain/bias resident)
# speedup vs baseline: 1.0112x; 1.0068x over previous
.LBB0_279:
	v_readlane_b32 s28, v250, 53
	s_nop 3
	s_cmp_eq_u32 s28, 3
	s_cbranch_scc1 .Lepi_A_final
	v_lshl_add_u32 v136, s58, 8, v158
	v_lshl_or_b32 v137, s2, 8, v159
	v_lshlrev_b32_e32 v136, 3, v136
	v_lshlrev_b32_e32 v137, 2, v137
	s_ashr_i32 s59, s58, 31
	s_lshl_b64 s[28:29], s[58:59], 20
	s_add_u32 s60, s73, s28
	s_addc_u32 s61, s72, s29
	v_readlane_b32 s4, v252, 0
	v_readlane_b32 s5, v252, 1
	v_readlane_b32 s6, v252, 2
	v_readlane_b32 s7, v252, 3
	v_readlane_b32 s8, v252, 4
	v_readlane_b32 s9, v252, 5
	v_readlane_b32 s10, v252, 6
	v_readlane_b32 s11, v252, 7
	v_readlane_b32 s12, v252, 8
	v_readlane_b32 s13, v252, 9
	v_readlane_b32 s14, v252, 10
	v_readlane_b32 s15, v252, 11
	v_readlane_b32 s16, v252, 12
	v_readlane_b32 s17, v252, 13
	s_mov_b64 s[4:5], s[8:9]
	v_readlane_b32 s18, v252, 14
	v_readlane_b32 s19, v252, 15
	s_mov_b64 s[6:7], s[10:11]
	s_mov_b64 s[8:9], s[12:13]
	s_mov_b64 s[12:13], s[16:17]
	s_add_u32 s58, s12, s28
	s_addc_u32 s59, s13, s29
	s_mov_b64 s[14:15], s[18:19]
	s_and_b64 vcc, exec, s[80:81]
	s_cbranch_vccz .Lepi_A_nostats
	s_mov_b64 s[40:41], 0
	global_load_dwordx2 v[240:241], v136, s[92:93]
	global_load_dwordx2 v[242:243], v136, s[92:93] offset:128
	global_load_dwordx2 v[244:245], v136, s[92:93] offset:256
	global_load_dwordx2 v[246:247], v136, s[92:93] offset:384
	global_load_dwordx2 v[248:249], v136, s[92:93] offset:1024
	global_load_dwordx2 v[220:221], v136, s[92:93] offset:1152
	global_load_dwordx2 v[108:109], v136, s[92:93] offset:1280
	global_load_dwordx2 v[110:111], v136, s[92:93] offset:1408
	global_load_dwordx4 v[196:199], v137, s[48:49]
	global_load_dwordx4 v[200:203], v137, s[84:85]
	global_load_dwordx4 v[204:207], v137, s[48:49] offset:64
	global_load_dwordx4 v[208:211], v137, s[84:85] offset:64
	global_load_dwordx4 v[212:215], v137, s[48:49] offset:512
	global_load_dwordx4 v[216:219], v137, s[84:85] offset:512
	global_load_dwordx4 v[232:235], v137, s[48:49] offset:576
	global_load_dwordx4 v[236:239], v137, s[84:85] offset:576
	v_lshl_add_u32 v112, v160, 2, v137
	v_lshl_add_u32 v113, v164, 2, v137
	v_lshl_add_u32 v130, v166, 2, v137
	v_lshl_add_u32 v131, v168, 2, v137
	v_lshl_add_u32 v132, v162, 2, v137
	v_lshl_add_u32 v133, v170, 2, v137
	v_lshl_add_u32 v134, v172, 2, v137
	v_lshl_add_u32 v135, v174, 2, v137
	global_load_dwordx4 v[180:183], v112, s[60:61]
	global_load_dwordx4 v[184:187], v112, s[60:61] offset:64
	global_load_dwordx4 v[188:191], v113, s[60:61]
	global_load_dwordx4 v[192:195], v113, s[60:61] offset:64
	s_waitcnt vmcnt(3)
	v_pk_add_f32 v[180:181], v[180:181], v[240:241] op_sel_hi:[1,0] neg_lo:[0,1] neg_hi:[0,1]
	v_pk_add_f32 v[182:183], v[182:183], v[240:241] op_sel_hi:[1,0] neg_lo:[0,1] neg_hi:[0,1]
	v_pk_mul_f32 v[180:181], v[180:181], v[240:241] op_sel:[0,1] op_sel_hi:[1,1]
	v_pk_mul_f32 v[182:183], v[182:183], v[240:241] op_sel:[0,1] op_sel_hi:[1,1]
	v_pk_fma_f32 v[180:181], v[196:197], v[180:181], v[200:201]
	v_pk_fma_f32 v[182:183], v[198:199], v[182:183], v[202:203]
	v_pk_mul_f32 v[180:181], v[180:181], s[82:83] op_sel_hi:[1,0]
	v_pk_mul_f32 v[182:183], v[182:183], s[82:83] op_sel_hi:[1,0]
	v_pk_fma_f32 v[138:139], v[138:139], 0.5, v[180:181] op_sel_hi:[1,0,1]
	v_pk_fma_f32 v[140:141], v[140:141], 0.5, v[182:183] op_sel_hi:[1,0,1]
	s_nop 0
	global_store_dwordx4 v112, v[138:141], s[58:59] sc1
	global_load_dwordx4 v[180:183], v130, s[60:61]
	s_waitcnt vmcnt(4)
	v_pk_add_f32 v[184:185], v[184:185], v[240:241] op_sel_hi:[1,0] neg_lo:[0,1] neg_hi:[0,1]
	v_pk_add_f32 v[186:187], v[186:187], v[240:241] op_sel_hi:[1,0] neg_lo:[0,1] neg_hi:[0,1]
	v_pk_mul_f32 v[184:185], v[184:185], v[240:241] op_sel:[0,1] op_sel_hi:[1,1]
	v_pk_mul_f32 v[186:187], v[186:187], v[240:241] op_sel:[0,1] op_sel_hi:[1,1]
	v_pk_fma_f32 v[184:185], v[204:205], v[184:185], v[208:209]
	v_pk_fma_f32 v[186:187], v[206:207], v[186:187], v[210:211]
	v_pk_mul_f32 v[184:185], v[184:185], s[82:83] op_sel_hi:[1,0]
	v_pk_mul_f32 v[186:187], v[186:187], s[82:83] op_sel_hi:[1,0]
	v_pk_fma_f32 v[92:93], v[92:93], 0.5, v[184:185] op_sel_hi:[1,0,1]
	v_pk_fma_f32 v[94:95], v[94:95], 0.5, v[186:187] op_sel_hi:[1,0,1]
	s_nop 0
	global_store_dwordx4 v112, v[92:95], s[58:59] offset:64 sc1
	global_load_dwordx4 v[184:187], v130, s[60:61] offset:64
	s_waitcnt vmcnt(5)
	v_pk_add_f32 v[188:189], v[188:189], v[242:243] op_sel_hi:[1,0] neg_lo:[0,1] neg_hi:[0,1]
	v_pk_add_f32 v[190:191], v[190:191], v[242:243] op_sel_hi:[1,0] neg_lo:[0,1] neg_hi:[0,1]
	v_pk_mul_f32 v[188:189], v[188:189], v[242:243] op_sel:[0,1] op_sel_hi:[1,1]
	v_pk_mul_f32 v[190:191], v[190:191], v[242:243] op_sel:[0,1] op_sel_hi:[1,1]
	v_pk_fma_f32 v[188:189], v[196:197], v[188:189], v[200:201]
	v_pk_fma_f32 v[190:191], v[198:199], v[190:191], v[202:203]
	v_pk_mul_f32 v[188:189], v[188:189], s[82:83] op_sel_hi:[1,0]
	v_pk_mul_f32 v[190:191], v[190:191], s[82:83] op_sel_hi:[1,0]
	v_pk_fma_f32 v[126:127], v[126:127], 0.5, v[188:189] op_sel_hi:[1,0,1]
	v_pk_fma_f32 v[128:129], v[128:129], 0.5, v[190:191] op_sel_hi:[1,0,1]
	s_nop 0
	global_store_dwordx4 v113, v[126:129], s[58:59] sc1
	global_load_dwordx4 v[188:191], v131, s[60:61]
	s_waitcnt vmcnt(6)
	v_pk_add_f32 v[192:193], v[192:193], v[242:243] op_sel_hi:[1,0] neg_lo:[0,1] neg_hi:[0,1]
	v_pk_add_f32 v[194:195], v[194:195], v[242:243] op_sel_hi:[1,0] neg_lo:[0,1] neg_hi:[0,1]
	v_pk_mul_f32 v[192:193], v[192:193], v[242:243] op_sel:[0,1] op_sel_hi:[1,1]
	v_pk_mul_f32 v[194:195], v[194:195], v[242:243] op_sel:[0,1] op_sel_hi:[1,1]
	v_pk_fma_f32 v[192:193], v[204:205], v[192:193], v[208:209]
	v_pk_fma_f32 v[194:195], v[206:207], v[194:195], v[210:211]
	v_pk_mul_f32 v[192:193], v[192:193], s[82:83] op_sel_hi:[1,0]
	v_pk_mul_f32 v[194:195], v[194:195], s[82:83] op_sel_hi:[1,0]
	v_pk_fma_f32 v[88:89], v[88:89], 0.5, v[192:193] op_sel_hi:[1,0,1]
	v_pk_fma_f32 v[90:91], v[90:91], 0.5, v[194:195] op_sel_hi:[1,0,1]
	s_nop 0
	global_store_dwordx4 v113, v[88:91], s[58:59] offset:64 sc1
	global_load_dwordx4 v[192:195], v131, s[60:61] offset:64
	s_waitcnt vmcnt(6)
	v_pk_add_f32 v[180:181], v[180:181], v[244:245] op_sel_hi:[1,0] neg_lo:[0,1] neg_hi:[0,1]
	v_pk_add_f32 v[182:183], v[182:183], v[244:245] op_sel_hi:[1,0] neg_lo:[0,1] neg_hi:[0,1]
	v_pk_mul_f32 v[180:181], v[180:181], v[244:245] op_sel:[0,1] op_sel_hi:[1,1]
	v_pk_mul_f32 v[182:183], v[182:183], v[244:245] op_sel:[0,1] op_sel_hi:[1,1]
	v_pk_fma_f32 v[180:181], v[196:197], v[180:181], v[200:201]
	v_pk_fma_f32 v[182:183], v[198:199], v[182:183], v[202:203]
	v_pk_mul_f32 v[180:181], v[180:181], s[82:83] op_sel_hi:[1,0]
	v_pk_mul_f32 v[182:183], v[182:183], s[82:83] op_sel_hi:[1,0]
	v_pk_fma_f32 v[122:123], v[122:123], 0.5, v[180:181] op_sel_hi:[1,0,1]
	v_pk_fma_f32 v[124:125], v[124:125], 0.5, v[182:183] op_sel_hi:[1,0,1]
	s_nop 0
	global_store_dwordx4 v130, v[122:125], s[58:59] sc1
	global_load_dwordx4 v[180:183], v132, s[60:61]
	s_waitcnt vmcnt(6)
	v_pk_add_f32 v[184:185], v[184:185], v[244:245] op_sel_hi:[1,0] neg_lo:[0,1] neg_hi:[0,1]
	v_pk_add_f32 v[186:187], v[186:187], v[244:245] op_sel_hi:[1,0] neg_lo:[0,1] neg_hi:[0,1]
	v_pk_mul_f32 v[184:185], v[184:185], v[244:245] op_sel:[0,1] op_sel_hi:[1,1]
	v_pk_mul_f32 v[186:187], v[186:187], v[244:245] op_sel:[0,1] op_sel_hi:[1,1]
	v_pk_fma_f32 v[184:185], v[204:205], v[184:185], v[208:209]
	v_pk_fma_f32 v[186:187], v[206:207], v[186:187], v[210:211]
	v_pk_mul_f32 v[184:185], v[184:185], s[82:83] op_sel_hi:[1,0]
	v_pk_mul_f32 v[186:187], v[186:187], s[82:83] op_sel_hi:[1,0]
	v_pk_fma_f32 v[84:85], v[84:85], 0.5, v[184:185] op_sel_hi:[1,0,1]
	v_pk_fma_f32 v[86:87], v[86:87], 0.5, v[186:187] op_sel_hi:[1,0,1]
	s_nop 0
	global_store_dwordx4 v130, v[84:87], s[58:59] offset:64 sc1
	global_load_dwordx4 v[184:187], v132, s[60:61] offset:64
	s_waitcnt vmcnt(6)
	v_pk_add_f32 v[188:189], v[188:189], v[246:247] op_sel_hi:[1,0] neg_lo:[0,1] neg_hi:[0,1]
	v_pk_add_f32 v[190:191], v[190:191], v[246:247] op_sel_hi:[1,0] neg_lo:[0,1] neg_hi:[0,1]
	v_pk_mul_f32 v[188:189], v[188:189], v[246:247] op_sel:[0,1] op_sel_hi:[1,1]
	v_pk_mul_f32 v[190:191], v[190:191], v[246:247] op_sel:[0,1] op_sel_hi:[1,1]
	v_pk_fma_f32 v[188:189], v[196:197], v[188:189], v[200:201]
	v_pk_fma_f32 v[190:191], v[198:199], v[190:191], v[202:203]
	v_pk_mul_f32 v[188:189], v[188:189], s[82:83] op_sel_hi:[1,0]
	v_pk_mul_f32 v[190:191], v[190:191], s[82:83] op_sel_hi:[1,0]
	v_pk_fma_f32 v[118:119], v[118:119], 0.5, v[188:189] op_sel_hi:[1,0,1]
	v_pk_fma_f32 v[120:121], v[120:121], 0.5, v[190:191] op_sel_hi:[1,0,1]
	s_nop 0
	global_store_dwordx4 v131, v[118:121], s[58:59] sc1
	global_load_dwordx4 v[188:191], v133, s[60:61]
	s_waitcnt vmcnt(6)
	v_pk_add_f32 v[192:193], v[192:193], v[246:247] op_sel_hi:[1,0] neg_lo:[0,1] neg_hi:[0,1]
	v_pk_add_f32 v[194:195], v[194:195], v[246:247] op_sel_hi:[1,0] neg_lo:[0,1] neg_hi:[0,1]
	v_pk_mul_f32 v[192:193], v[192:193], v[246:247] op_sel:[0,1] op_sel_hi:[1,1]
	v_pk_mul_f32 v[194:195], v[194:195], v[246:247] op_sel:[0,1] op_sel_hi:[1,1]
	v_pk_fma_f32 v[192:193], v[204:205], v[192:193], v[208:209]
	v_pk_fma_f32 v[194:195], v[206:207], v[194:195], v[210:211]
	v_pk_mul_f32 v[192:193], v[192:193], s[82:83] op_sel_hi:[1,0]
	v_pk_mul_f32 v[194:195], v[194:195], s[82:83] op_sel_hi:[1,0]
	v_pk_fma_f32 v[80:81], v[80:81], 0.5, v[192:193] op_sel_hi:[1,0,1]
	v_pk_fma_f32 v[82:83], v[82:83], 0.5, v[194:195] op_sel_hi:[1,0,1]
	s_nop 0
	global_store_dwordx4 v131, v[80:83], s[58:59] offset:64 sc1
	global_load_dwordx4 v[192:195], v133, s[60:61] offset:64
	s_waitcnt vmcnt(6)
	v_pk_add_f32 v[180:181], v[180:181], v[248:249] op_sel_hi:[1,0] neg_lo:[0,1] neg_hi:[0,1]
	v_pk_add_f32 v[182:183], v[182:183], v[248:249] op_sel_hi:[1,0] neg_lo:[0,1] neg_hi:[0,1]
	v_pk_mul_f32 v[180:181], v[180:181], v[248:249] op_sel:[0,1] op_sel_hi:[1,1]
	v_pk_mul_f32 v[182:183], v[182:183], v[248:249] op_sel:[0,1] op_sel_hi:[1,1]
	v_pk_fma_f32 v[180:181], v[196:197], v[180:181], v[200:201]
	v_pk_fma_f32 v[182:183], v[198:199], v[182:183], v[202:203]
	v_pk_mul_f32 v[180:181], v[180:181], s[82:83] op_sel_hi:[1,0]
	v_pk_mul_f32 v[182:183], v[182:183], s[82:83] op_sel_hi:[1,0]
	v_pk_fma_f32 v[114:115], v[114:115], 0.5, v[180:181] op_sel_hi:[1,0,1]
	v_pk_fma_f32 v[116:117], v[116:117], 0.5, v[182:183] op_sel_hi:[1,0,1]
	s_nop 0
	global_store_dwordx4 v132, v[114:117], s[58:59] sc1
	global_load_dwordx4 v[180:183], v134, s[60:61]
	s_waitcnt vmcnt(6)
	v_pk_add_f32 v[184:185], v[184:185], v[248:249] op_sel_hi:[1,0] neg_lo:[0,1] neg_hi:[0,1]
	v_pk_add_f32 v[186:187], v[186:187], v[248:249] op_sel_hi:[1,0] neg_lo:[0,1] neg_hi:[0,1]
	v_pk_mul_f32 v[184:185], v[184:185], v[248:249] op_sel:[0,1] op_sel_hi:[1,1]
	v_pk_mul_f32 v[186:187], v[186:187], v[248:249] op_sel:[0,1] op_sel_hi:[1,1]
	v_pk_fma_f32 v[184:185], v[204:205], v[184:185], v[208:209]
	v_pk_fma_f32 v[186:187], v[206:207], v[186:187], v[210:211]
	v_pk_mul_f32 v[184:185], v[184:185], s[82:83] op_sel_hi:[1,0]
	v_pk_mul_f32 v[186:187], v[186:187], s[82:83] op_sel_hi:[1,0]
	v_pk_fma_f32 v[76:77], v[76:77], 0.5, v[184:185] op_sel_hi:[1,0,1]
	v_pk_fma_f32 v[78:79], v[78:79], 0.5, v[186:187] op_sel_hi:[1,0,1]
	s_nop 0
	global_store_dwordx4 v132, v[76:79], s[58:59] offset:64 sc1
	global_load_dwordx4 v[184:187], v134, s[60:61] offset:64
	s_waitcnt vmcnt(6)
	v_pk_add_f32 v[188:189], v[188:189], v[220:221] op_sel_hi:[1,0] neg_lo:[0,1] neg_hi:[0,1]
	v_pk_add_f32 v[190:191], v[190:191], v[220:221] op_sel_hi:[1,0] neg_lo:[0,1] neg_hi:[0,1]
	v_pk_mul_f32 v[188:189], v[188:189], v[220:221] op_sel:[0,1] op_sel_hi:[1,1]
	v_pk_mul_f32 v[190:191], v[190:191], v[220:221] op_sel:[0,1] op_sel_hi:[1,1]
	v_pk_fma_f32 v[188:189], v[196:197], v[188:189], v[200:201]
	v_pk_fma_f32 v[190:191], v[198:199], v[190:191], v[202:203]
	v_pk_mul_f32 v[188:189], v[188:189], s[82:83] op_sel_hi:[1,0]
	v_pk_mul_f32 v[190:191], v[190:191], s[82:83] op_sel_hi:[1,0]
	v_pk_fma_f32 v[104:105], v[104:105], 0.5, v[188:189] op_sel_hi:[1,0,1]
	v_pk_fma_f32 v[106:107], v[106:107], 0.5, v[190:191] op_sel_hi:[1,0,1]
	s_nop 0
	global_store_dwordx4 v133, v[104:107], s[58:59] sc1
	global_load_dwordx4 v[188:191], v135, s[60:61]
	s_waitcnt vmcnt(6)
	v_pk_add_f32 v[192:193], v[192:193], v[220:221] op_sel_hi:[1,0] neg_lo:[0,1] neg_hi:[0,1]
	v_pk_add_f32 v[194:195], v[194:195], v[220:221] op_sel_hi:[1,0] neg_lo:[0,1] neg_hi:[0,1]
	v_pk_mul_f32 v[192:193], v[192:193], v[220:221] op_sel:[0,1] op_sel_hi:[1,1]
	v_pk_mul_f32 v[194:195], v[194:195], v[220:221] op_sel:[0,1] op_sel_hi:[1,1]
	v_pk_fma_f32 v[192:193], v[204:205], v[192:193], v[208:209]
	v_pk_fma_f32 v[194:195], v[206:207], v[194:195], v[210:211]
	v_pk_mul_f32 v[192:193], v[192:193], s[82:83] op_sel_hi:[1,0]
	v_pk_mul_f32 v[194:195], v[194:195], s[82:83] op_sel_hi:[1,0]
	v_pk_fma_f32 v[72:73], v[72:73], 0.5, v[192:193] op_sel_hi:[1,0,1]
	v_pk_fma_f32 v[74:75], v[74:75], 0.5, v[194:195] op_sel_hi:[1,0,1]
	s_nop 0
	global_store_dwordx4 v133, v[72:75], s[58:59] offset:64 sc1
	global_load_dwordx4 v[192:195], v135, s[60:61] offset:64
	s_waitcnt vmcnt(6)
	v_pk_add_f32 v[180:181], v[180:181], v[108:109] op_sel_hi:[1,0] neg_lo:[0,1] neg_hi:[0,1]
	v_pk_add_f32 v[182:183], v[182:183], v[108:109] op_sel_hi:[1,0] neg_lo:[0,1] neg_hi:[0,1]
	v_pk_mul_f32 v[180:181], v[180:181], v[108:109] op_sel:[0,1] op_sel_hi:[1,1]
	v_pk_mul_f32 v[182:183], v[182:183], v[108:109] op_sel:[0,1] op_sel_hi:[1,1]
	v_pk_fma_f32 v[180:181], v[196:197], v[180:181], v[200:201]
	v_pk_fma_f32 v[182:183], v[198:199], v[182:183], v[202:203]
	v_pk_mul_f32 v[180:181], v[180:181], s[82:83] op_sel_hi:[1,0]
	v_pk_mul_f32 v[182:183], v[182:183], s[82:83] op_sel_hi:[1,0]
	v_pk_fma_f32 v[100:101], v[100:101], 0.5, v[180:181] op_sel_hi:[1,0,1]
	v_pk_fma_f32 v[102:103], v[102:103], 0.5, v[182:183] op_sel_hi:[1,0,1]
	s_nop 0
	global_store_dwordx4 v134, v[100:103], s[58:59] sc1
	global_load_dwordx4 v[180:183], v112, s[60:61] offset:512
	s_waitcnt vmcnt(6)
	v_pk_add_f32 v[184:185], v[184:185], v[108:109] op_sel_hi:[1,0] neg_lo:[0,1] neg_hi:[0,1]
	v_pk_add_f32 v[186:187], v[186:187], v[108:109] op_sel_hi:[1,0] neg_lo:[0,1] neg_hi:[0,1]
	v_pk_mul_f32 v[184:185], v[184:185], v[108:109] op_sel:[0,1] op_sel_hi:[1,1]
	v_pk_mul_f32 v[186:187], v[186:187], v[108:109] op_sel:[0,1] op_sel_hi:[1,1]
	v_pk_fma_f32 v[184:185], v[204:205], v[184:185], v[208:209]
	v_pk_fma_f32 v[186:187], v[206:207], v[186:187], v[210:211]
	v_pk_mul_f32 v[184:185], v[184:185], s[82:83] op_sel_hi:[1,0]
	v_pk_mul_f32 v[186:187], v[186:187], s[82:83] op_sel_hi:[1,0]
	v_pk_fma_f32 v[68:69], v[68:69], 0.5, v[184:185] op_sel_hi:[1,0,1]
	v_pk_fma_f32 v[70:71], v[70:71], 0.5, v[186:187] op_sel_hi:[1,0,1]
	s_nop 0
	global_store_dwordx4 v134, v[68:71], s[58:59] offset:64 sc1
	global_load_dwordx4 v[184:187], v112, s[60:61] offset:576
	s_waitcnt vmcnt(6)
	v_pk_add_f32 v[188:189], v[188:189], v[110:111] op_sel_hi:[1,0] neg_lo:[0,1] neg_hi:[0,1]
	v_pk_add_f32 v[190:191], v[190:191], v[110:111] op_sel_hi:[1,0] neg_lo:[0,1] neg_hi:[0,1]
	v_pk_mul_f32 v[188:189], v[188:189], v[110:111] op_sel:[0,1] op_sel_hi:[1,1]
	v_pk_mul_f32 v[190:191], v[190:191], v[110:111] op_sel:[0,1] op_sel_hi:[1,1]
	v_pk_fma_f32 v[188:189], v[196:197], v[188:189], v[200:201]
	v_pk_fma_f32 v[190:191], v[198:199], v[190:191], v[202:203]
	v_pk_mul_f32 v[188:189], v[188:189], s[82:83] op_sel_hi:[1,0]
	v_pk_mul_f32 v[190:191], v[190:191], s[82:83] op_sel_hi:[1,0]
	v_pk_fma_f32 v[96:97], v[96:97], 0.5, v[188:189] op_sel_hi:[1,0,1]
	v_pk_fma_f32 v[98:99], v[98:99], 0.5, v[190:191] op_sel_hi:[1,0,1]
	s_nop 0
	global_store_dwordx4 v135, v[96:99], s[58:59] sc1
	global_load_dwordx4 v[188:191], v113, s[60:61] offset:512
	s_waitcnt vmcnt(6)
	v_pk_add_f32 v[192:193], v[192:193], v[110:111] op_sel_hi:[1,0] neg_lo:[0,1] neg_hi:[0,1]
	v_pk_add_f32 v[194:195], v[194:195], v[110:111] op_sel_hi:[1,0] neg_lo:[0,1] neg_hi:[0,1]
	v_pk_mul_f32 v[192:193], v[192:193], v[110:111] op_sel:[0,1] op_sel_hi:[1,1]
	v_pk_mul_f32 v[194:195], v[194:195], v[110:111] op_sel:[0,1] op_sel_hi:[1,1]
	v_pk_fma_f32 v[192:193], v[204:205], v[192:193], v[208:209]
	v_pk_fma_f32 v[194:195], v[206:207], v[194:195], v[210:211]
	v_pk_mul_f32 v[192:193], v[192:193], s[82:83] op_sel_hi:[1,0]
	v_pk_mul_f32 v[194:195], v[194:195], s[82:83] op_sel_hi:[1,0]
	v_pk_fma_f32 v[64:65], v[64:65], 0.5, v[192:193] op_sel_hi:[1,0,1]
	v_pk_fma_f32 v[66:67], v[66:67], 0.5, v[194:195] op_sel_hi:[1,0,1]
	s_nop 0
	global_store_dwordx4 v135, v[64:67], s[58:59] offset:64 sc1
	global_load_dwordx4 v[192:195], v113, s[60:61] offset:576
	s_waitcnt vmcnt(6)
	v_pk_add_f32 v[180:181], v[180:181], v[240:241] op_sel_hi:[1,0] neg_lo:[0,1] neg_hi:[0,1]
	v_pk_add_f32 v[182:183], v[182:183], v[240:241] op_sel_hi:[1,0] neg_lo:[0,1] neg_hi:[0,1]
	v_pk_mul_f32 v[180:181], v[180:181], v[240:241] op_sel:[0,1] op_sel_hi:[1,1]
	v_pk_mul_f32 v[182:183], v[182:183], v[240:241] op_sel:[0,1] op_sel_hi:[1,1]
	v_pk_fma_f32 v[180:181], v[212:213], v[180:181], v[216:217]
	v_pk_fma_f32 v[182:183], v[214:215], v[182:183], v[218:219]
	v_pk_mul_f32 v[180:181], v[180:181], s[82:83] op_sel_hi:[1,0]
	v_pk_mul_f32 v[182:183], v[182:183], s[82:83] op_sel_hi:[1,0]
	v_pk_fma_f32 v[60:61], v[60:61], 0.5, v[180:181] op_sel_hi:[1,0,1]
	v_pk_fma_f32 v[62:63], v[62:63], 0.5, v[182:183] op_sel_hi:[1,0,1]
	s_nop 0
	global_store_dwordx4 v112, v[60:63], s[58:59] offset:512 sc1
	global_load_dwordx4 v[180:183], v130, s[60:61] offset:512
	s_waitcnt vmcnt(6)
	v_pk_add_f32 v[184:185], v[184:185], v[240:241] op_sel_hi:[1,0] neg_lo:[0,1] neg_hi:[0,1]
	v_pk_add_f32 v[186:187], v[186:187], v[240:241] op_sel_hi:[1,0] neg_lo:[0,1] neg_hi:[0,1]
	v_pk_mul_f32 v[184:185], v[184:185], v[240:241] op_sel:[0,1] op_sel_hi:[1,1]
	v_pk_mul_f32 v[186:187], v[186:187], v[240:241] op_sel:[0,1] op_sel_hi:[1,1]
	v_pk_fma_f32 v[184:185], v[232:233], v[184:185], v[236:237]
	v_pk_fma_f32 v[186:187], v[234:235], v[186:187], v[238:239]
	v_pk_mul_f32 v[184:185], v[184:185], s[82:83] op_sel_hi:[1,0]
	v_pk_mul_f32 v[186:187], v[186:187], s[82:83] op_sel_hi:[1,0]
	v_pk_fma_f32 v[28:29], v[28:29], 0.5, v[184:185] op_sel_hi:[1,0,1]
	v_pk_fma_f32 v[30:31], v[30:31], 0.5, v[186:187] op_sel_hi:[1,0,1]
	s_nop 0
	global_store_dwordx4 v112, v[28:31], s[58:59] offset:576 sc1
	global_load_dwordx4 v[184:187], v130, s[60:61] offset:576
	s_waitcnt vmcnt(6)
	v_pk_add_f32 v[188:189], v[188:189], v[242:243] op_sel_hi:[1,0] neg_lo:[0,1] neg_hi:[0,1]
	v_pk_add_f32 v[190:191], v[190:191], v[242:243] op_sel_hi:[1,0] neg_lo:[0,1] neg_hi:[0,1]
	v_pk_mul_f32 v[188:189], v[188:189], v[242:243] op_sel:[0,1] op_sel_hi:[1,1]
	v_pk_mul_f32 v[190:191], v[190:191], v[242:243] op_sel:[0,1] op_sel_hi:[1,1]
	v_pk_fma_f32 v[188:189], v[212:213], v[188:189], v[216:217]
	v_pk_fma_f32 v[190:191], v[214:215], v[190:191], v[218:219]
	v_pk_mul_f32 v[188:189], v[188:189], s[82:83] op_sel_hi:[1,0]
	v_pk_mul_f32 v[190:191], v[190:191], s[82:83] op_sel_hi:[1,0]
	v_pk_fma_f32 v[56:57], v[56:57], 0.5, v[188:189] op_sel_hi:[1,0,1]
	v_pk_fma_f32 v[58:59], v[58:59], 0.5, v[190:191] op_sel_hi:[1,0,1]
	s_nop 0
	global_store_dwordx4 v113, v[56:59], s[58:59] offset:512 sc1
	global_load_dwordx4 v[188:191], v131, s[60:61] offset:512
	s_waitcnt vmcnt(6)
	v_pk_add_f32 v[192:193], v[192:193], v[242:243] op_sel_hi:[1,0] neg_lo:[0,1] neg_hi:[0,1]
	v_pk_add_f32 v[194:195], v[194:195], v[242:243] op_sel_hi:[1,0] neg_lo:[0,1] neg_hi:[0,1]
	v_pk_mul_f32 v[192:193], v[192:193], v[242:243] op_sel:[0,1] op_sel_hi:[1,1]
	v_pk_mul_f32 v[194:195], v[194:195], v[242:243] op_sel:[0,1] op_sel_hi:[1,1]
	v_pk_fma_f32 v[192:193], v[232:233], v[192:193], v[236:237]
	v_pk_fma_f32 v[194:195], v[234:235], v[194:195], v[238:239]
	v_pk_mul_f32 v[192:193], v[192:193], s[82:83] op_sel_hi:[1,0]
	v_pk_mul_f32 v[194:195], v[194:195], s[82:83] op_sel_hi:[1,0]
	v_pk_fma_f32 v[24:25], v[24:25], 0.5, v[192:193] op_sel_hi:[1,0,1]
	v_pk_fma_f32 v[26:27], v[26:27], 0.5, v[194:195] op_sel_hi:[1,0,1]
	s_nop 0
	global_store_dwordx4 v113, v[24:27], s[58:59] offset:576 sc1
	global_load_dwordx4 v[192:195], v131, s[60:61] offset:576
	s_waitcnt vmcnt(6)
	v_pk_add_f32 v[180:181], v[180:181], v[244:245] op_sel_hi:[1,0] neg_lo:[0,1] neg_hi:[0,1]
	v_pk_add_f32 v[182:183], v[182:183], v[244:245] op_sel_hi:[1,0] neg_lo:[0,1] neg_hi:[0,1]
	v_pk_mul_f32 v[180:181], v[180:181], v[244:245] op_sel:[0,1] op_sel_hi:[1,1]
	v_pk_mul_f32 v[182:183], v[182:183], v[244:245] op_sel:[0,1] op_sel_hi:[1,1]
	v_pk_fma_f32 v[180:181], v[212:213], v[180:181], v[216:217]
	v_pk_fma_f32 v[182:183], v[214:215], v[182:183], v[218:219]
	v_pk_mul_f32 v[180:181], v[180:181], s[82:83] op_sel_hi:[1,0]
	v_pk_mul_f32 v[182:183], v[182:183], s[82:83] op_sel_hi:[1,0]
	v_pk_fma_f32 v[52:53], v[52:53], 0.5, v[180:181] op_sel_hi:[1,0,1]
	v_pk_fma_f32 v[54:55], v[54:55], 0.5, v[182:183] op_sel_hi:[1,0,1]
	s_nop 0
	global_store_dwordx4 v130, v[52:55], s[58:59] offset:512 sc1
	global_load_dwordx4 v[180:183], v132, s[60:61] offset:512
	s_waitcnt vmcnt(6)
	v_pk_add_f32 v[184:185], v[184:185], v[244:245] op_sel_hi:[1,0] neg_lo:[0,1] neg_hi:[0,1]
	v_pk_add_f32 v[186:187], v[186:187], v[244:245] op_sel_hi:[1,0] neg_lo:[0,1] neg_hi:[0,1]
	v_pk_mul_f32 v[184:185], v[184:185], v[244:245] op_sel:[0,1] op_sel_hi:[1,1]
	v_pk_mul_f32 v[186:187], v[186:187], v[244:245] op_sel:[0,1] op_sel_hi:[1,1]
	v_pk_fma_f32 v[184:185], v[232:233], v[184:185], v[236:237]
	v_pk_fma_f32 v[186:187], v[234:235], v[186:187], v[238:239]
	v_pk_mul_f32 v[184:185], v[184:185], s[82:83] op_sel_hi:[1,0]
	v_pk_mul_f32 v[186:187], v[186:187], s[82:83] op_sel_hi:[1,0]
	v_pk_fma_f32 v[20:21], v[20:21], 0.5, v[184:185] op_sel_hi:[1,0,1]
	v_pk_fma_f32 v[22:23], v[22:23], 0.5, v[186:187] op_sel_hi:[1,0,1]
	s_nop 0
	global_store_dwordx4 v130, v[20:23], s[58:59] offset:576 sc1
	global_load_dwordx4 v[184:187], v132, s[60:61] offset:576
	s_waitcnt vmcnt(6)
	v_pk_add_f32 v[188:189], v[188:189], v[246:247] op_sel_hi:[1,0] neg_lo:[0,1] neg_hi:[0,1]
	v_pk_add_f32 v[190:191], v[190:191], v[246:247] op_sel_hi:[1,0] neg_lo:[0,1] neg_hi:[0,1]
	v_pk_mul_f32 v[188:189], v[188:189], v[246:247] op_sel:[0,1] op_sel_hi:[1,1]
	v_pk_mul_f32 v[190:191], v[190:191], v[246:247] op_sel:[0,1] op_sel_hi:[1,1]
	v_pk_fma_f32 v[188:189], v[212:213], v[188:189], v[216:217]
	v_pk_fma_f32 v[190:191], v[214:215], v[190:191], v[218:219]
	v_pk_mul_f32 v[188:189], v[188:189], s[82:83] op_sel_hi:[1,0]
	v_pk_mul_f32 v[190:191], v[190:191], s[82:83] op_sel_hi:[1,0]
	v_pk_fma_f32 v[48:49], v[48:49], 0.5, v[188:189] op_sel_hi:[1,0,1]
	v_pk_fma_f32 v[50:51], v[50:51], 0.5, v[190:191] op_sel_hi:[1,0,1]
	s_nop 0
	global_store_dwordx4 v131, v[48:51], s[58:59] offset:512 sc1
	global_load_dwordx4 v[188:191], v133, s[60:61] offset:512
	s_waitcnt vmcnt(6)
	v_pk_add_f32 v[192:193], v[192:193], v[246:247] op_sel_hi:[1,0] neg_lo:[0,1] neg_hi:[0,1]
	v_pk_add_f32 v[194:195], v[194:195], v[246:247] op_sel_hi:[1,0] neg_lo:[0,1] neg_hi:[0,1]
	v_pk_mul_f32 v[192:193], v[192:193], v[246:247] op_sel:[0,1] op_sel_hi:[1,1]
	v_pk_mul_f32 v[194:195], v[194:195], v[246:247] op_sel:[0,1] op_sel_hi:[1,1]
	v_pk_fma_f32 v[192:193], v[232:233], v[192:193], v[236:237]
	v_pk_fma_f32 v[194:195], v[234:235], v[194:195], v[238:239]
	v_pk_mul_f32 v[192:193], v[192:193], s[82:83] op_sel_hi:[1,0]
	v_pk_mul_f32 v[194:195], v[194:195], s[82:83] op_sel_hi:[1,0]
	v_pk_fma_f32 v[16:17], v[16:17], 0.5, v[192:193] op_sel_hi:[1,0,1]
	v_pk_fma_f32 v[18:19], v[18:19], 0.5, v[194:195] op_sel_hi:[1,0,1]
	s_nop 0
	global_store_dwordx4 v131, v[16:19], s[58:59] offset:576 sc1
	global_load_dwordx4 v[192:195], v133, s[60:61] offset:576
	s_waitcnt vmcnt(6)
	v_pk_add_f32 v[180:181], v[180:181], v[248:249] op_sel_hi:[1,0] neg_lo:[0,1] neg_hi:[0,1]
	v_pk_add_f32 v[182:183], v[182:183], v[248:249] op_sel_hi:[1,0] neg_lo:[0,1] neg_hi:[0,1]
	v_pk_mul_f32 v[180:181], v[180:181], v[248:249] op_sel:[0,1] op_sel_hi:[1,1]
	v_pk_mul_f32 v[182:183], v[182:183], v[248:249] op_sel:[0,1] op_sel_hi:[1,1]
	v_pk_fma_f32 v[180:181], v[212:213], v[180:181], v[216:217]
	v_pk_fma_f32 v[182:183], v[214:215], v[182:183], v[218:219]
	v_pk_mul_f32 v[180:181], v[180:181], s[82:83] op_sel_hi:[1,0]
	v_pk_mul_f32 v[182:183], v[182:183], s[82:83] op_sel_hi:[1,0]
	v_pk_fma_f32 v[44:45], v[44:45], 0.5, v[180:181] op_sel_hi:[1,0,1]
	v_pk_fma_f32 v[46:47], v[46:47], 0.5, v[182:183] op_sel_hi:[1,0,1]
	s_nop 0
	global_store_dwordx4 v132, v[44:47], s[58:59] offset:512 sc1
	global_load_dwordx4 v[180:183], v134, s[60:61] offset:512
	s_waitcnt vmcnt(6)
	v_pk_add_f32 v[184:185], v[184:185], v[248:249] op_sel_hi:[1,0] neg_lo:[0,1] neg_hi:[0,1]
	v_pk_add_f32 v[186:187], v[186:187], v[248:249] op_sel_hi:[1,0] neg_lo:[0,1] neg_hi:[0,1]
	v_pk_mul_f32 v[184:185], v[184:185], v[248:249] op_sel:[0,1] op_sel_hi:[1,1]
	v_pk_mul_f32 v[186:187], v[186:187], v[248:249] op_sel:[0,1] op_sel_hi:[1,1]
	v_pk_fma_f32 v[184:185], v[232:233], v[184:185], v[236:237]
	v_pk_fma_f32 v[186:187], v[234:235], v[186:187], v[238:239]
	v_pk_mul_f32 v[184:185], v[184:185], s[82:83] op_sel_hi:[1,0]
	v_pk_mul_f32 v[186:187], v[186:187], s[82:83] op_sel_hi:[1,0]
	v_pk_fma_f32 v[12:13], v[12:13], 0.5, v[184:185] op_sel_hi:[1,0,1]
	v_pk_fma_f32 v[14:15], v[14:15], 0.5, v[186:187] op_sel_hi:[1,0,1]
	s_nop 0
	global_store_dwordx4 v132, v[12:15], s[58:59] offset:576 sc1
	global_load_dwordx4 v[184:187], v134, s[60:61] offset:576
	s_waitcnt vmcnt(6)
	v_pk_add_f32 v[188:189], v[188:189], v[220:221] op_sel_hi:[1,0] neg_lo:[0,1] neg_hi:[0,1]
	v_pk_add_f32 v[190:191], v[190:191], v[220:221] op_sel_hi:[1,0] neg_lo:[0,1] neg_hi:[0,1]
	v_pk_mul_f32 v[188:189], v[188:189], v[220:221] op_sel:[0,1] op_sel_hi:[1,1]
	v_pk_mul_f32 v[190:191], v[190:191], v[220:221] op_sel:[0,1] op_sel_hi:[1,1]
	v_pk_fma_f32 v[188:189], v[212:213], v[188:189], v[216:217]
	v_pk_fma_f32 v[190:191], v[214:215], v[190:191], v[218:219]
	v_pk_mul_f32 v[188:189], v[188:189], s[82:83] op_sel_hi:[1,0]
	v_pk_mul_f32 v[190:191], v[190:191], s[82:83] op_sel_hi:[1,0]
	v_pk_fma_f32 v[40:41], v[40:41], 0.5, v[188:189] op_sel_hi:[1,0,1]
	v_pk_fma_f32 v[42:43], v[42:43], 0.5, v[190:191] op_sel_hi:[1,0,1]
	s_nop 0
	global_store_dwordx4 v133, v[40:43], s[58:59] offset:512 sc1
	global_load_dwordx4 v[188:191], v135, s[60:61] offset:512
	s_waitcnt vmcnt(6)
	v_pk_add_f32 v[192:193], v[192:193], v[220:221] op_sel_hi:[1,0] neg_lo:[0,1] neg_hi:[0,1]
	v_pk_add_f32 v[194:195], v[194:195], v[220:221] op_sel_hi:[1,0] neg_lo:[0,1] neg_hi:[0,1]
	v_pk_mul_f32 v[192:193], v[192:193], v[220:221] op_sel:[0,1] op_sel_hi:[1,1]
	v_pk_mul_f32 v[194:195], v[194:195], v[220:221] op_sel:[0,1] op_sel_hi:[1,1]
	v_pk_fma_f32 v[192:193], v[232:233], v[192:193], v[236:237]
	v_pk_fma_f32 v[194:195], v[234:235], v[194:195], v[238:239]
	v_pk_mul_f32 v[192:193], v[192:193], s[82:83] op_sel_hi:[1,0]
	v_pk_mul_f32 v[194:195], v[194:195], s[82:83] op_sel_hi:[1,0]
	v_pk_fma_f32 v[8:9], v[8:9], 0.5, v[192:193] op_sel_hi:[1,0,1]
	v_pk_fma_f32 v[10:11], v[10:11], 0.5, v[194:195] op_sel_hi:[1,0,1]
	s_nop 0
	global_store_dwordx4 v133, v[8:11], s[58:59] offset:576 sc1
	global_load_dwordx4 v[192:195], v135, s[60:61] offset:576
	s_waitcnt vmcnt(6)
	v_pk_add_f32 v[180:181], v[180:181], v[108:109] op_sel_hi:[1,0] neg_lo:[0,1] neg_hi:[0,1]
	v_pk_add_f32 v[182:183], v[182:183], v[108:109] op_sel_hi:[1,0] neg_lo:[0,1] neg_hi:[0,1]
	v_pk_mul_f32 v[180:181], v[180:181], v[108:109] op_sel:[0,1] op_sel_hi:[1,1]
	v_pk_mul_f32 v[182:183], v[182:183], v[108:109] op_sel:[0,1] op_sel_hi:[1,1]
	v_pk_fma_f32 v[180:181], v[212:213], v[180:181], v[216:217]
	v_pk_fma_f32 v[182:183], v[214:215], v[182:183], v[218:219]
	v_pk_mul_f32 v[180:181], v[180:181], s[82:83] op_sel_hi:[1,0]
	v_pk_mul_f32 v[182:183], v[182:183], s[82:83] op_sel_hi:[1,0]
	v_pk_fma_f32 v[36:37], v[36:37], 0.5, v[180:181] op_sel_hi:[1,0,1]
	v_pk_fma_f32 v[38:39], v[38:39], 0.5, v[182:183] op_sel_hi:[1,0,1]
	s_nop 0
	global_store_dwordx4 v134, v[36:39], s[58:59] offset:512 sc1
	s_waitcnt vmcnt(5)
	v_pk_add_f32 v[184:185], v[184:185], v[108:109] op_sel_hi:[1,0] neg_lo:[0,1] neg_hi:[0,1]
	v_pk_add_f32 v[186:187], v[186:187], v[108:109] op_sel_hi:[1,0] neg_lo:[0,1] neg_hi:[0,1]
	v_pk_mul_f32 v[184:185], v[184:185], v[108:109] op_sel:[0,1] op_sel_hi:[1,1]
	v_pk_mul_f32 v[186:187], v[186:187], v[108:109] op_sel:[0,1] op_sel_hi:[1,1]
	v_pk_fma_f32 v[184:185], v[232:233], v[184:185], v[236:237]
	v_pk_fma_f32 v[186:187], v[234:235], v[186:187], v[238:239]
	v_pk_mul_f32 v[184:185], v[184:185], s[82:83] op_sel_hi:[1,0]
	v_pk_mul_f32 v[186:187], v[186:187], s[82:83] op_sel_hi:[1,0]
	v_pk_fma_f32 v[4:5], v[4:5], 0.5, v[184:185] op_sel_hi:[1,0,1]
	v_pk_fma_f32 v[6:7], v[6:7], 0.5, v[186:187] op_sel_hi:[1,0,1]
	s_nop 0
	global_store_dwordx4 v134, v[4:7], s[58:59] offset:576 sc1
	s_waitcnt vmcnt(4)
	v_pk_add_f32 v[188:189], v[188:189], v[110:111] op_sel_hi:[1,0] neg_lo:[0,1] neg_hi:[0,1]
	v_pk_add_f32 v[190:191], v[190:191], v[110:111] op_sel_hi:[1,0] neg_lo:[0,1] neg_hi:[0,1]
	v_pk_mul_f32 v[188:189], v[188:189], v[110:111] op_sel:[0,1] op_sel_hi:[1,1]
	v_pk_mul_f32 v[190:191], v[190:191], v[110:111] op_sel:[0,1] op_sel_hi:[1,1]
	v_pk_fma_f32 v[188:189], v[212:213], v[188:189], v[216:217]
	v_pk_fma_f32 v[190:191], v[214:215], v[190:191], v[218:219]
	v_pk_mul_f32 v[188:189], v[188:189], s[82:83] op_sel_hi:[1,0]
	v_pk_mul_f32 v[190:191], v[190:191], s[82:83] op_sel_hi:[1,0]
	v_pk_fma_f32 v[32:33], v[32:33], 0.5, v[188:189] op_sel_hi:[1,0,1]
	v_pk_fma_f32 v[34:35], v[34:35], 0.5, v[190:191] op_sel_hi:[1,0,1]
	s_nop 0
	global_store_dwordx4 v135, v[32:35], s[58:59] offset:512 sc1
	s_waitcnt vmcnt(3)
	v_pk_add_f32 v[192:193], v[192:193], v[110:111] op_sel_hi:[1,0] neg_lo:[0,1] neg_hi:[0,1]
	v_pk_add_f32 v[194:195], v[194:195], v[110:111] op_sel_hi:[1,0] neg_lo:[0,1] neg_hi:[0,1]
	v_pk_mul_f32 v[192:193], v[192:193], v[110:111] op_sel:[0,1] op_sel_hi:[1,1]
	v_pk_mul_f32 v[194:195], v[194:195], v[110:111] op_sel:[0,1] op_sel_hi:[1,1]
	v_pk_fma_f32 v[192:193], v[232:233], v[192:193], v[236:237]
	v_pk_fma_f32 v[194:195], v[234:235], v[194:195], v[238:239]
	v_pk_mul_f32 v[192:193], v[192:193], s[82:83] op_sel_hi:[1,0]
	v_pk_mul_f32 v[194:195], v[194:195], s[82:83] op_sel_hi:[1,0]
	v_pk_fma_f32 v[0:1], v[0:1], 0.5, v[192:193] op_sel_hi:[1,0,1]
	v_pk_fma_f32 v[2:3], v[2:3], 0.5, v[194:195] op_sel_hi:[1,0,1]
	s_nop 0
	global_store_dwordx4 v135, v[0:3], s[58:59] offset:576 sc1
	s_branch .Lepi_A_join
.Lepi_A_nostats:
	s_mov_b64 s[40:41], exec
	v_lshl_add_u32 v112, v160, 2, v137
	v_lshl_add_u32 v113, v164, 2, v137
	v_lshl_add_u32 v130, v166, 2, v137
	v_lshl_add_u32 v131, v168, 2, v137
	v_lshl_add_u32 v132, v162, 2, v137
	v_lshl_add_u32 v133, v170, 2, v137
	v_lshl_add_u32 v134, v172, 2, v137
	v_lshl_add_u32 v135, v174, 2, v137
	global_load_dwordx4 v[180:183], v112, s[60:61]
	global_load_dwordx4 v[184:187], v112, s[60:61] offset:64
	global_load_dwordx4 v[188:191], v113, s[60:61]
	global_load_dwordx4 v[192:195], v113, s[60:61] offset:64
	s_waitcnt vmcnt(3)
	v_pk_mul_f32 v[180:181], v[180:181], s[82:83] op_sel_hi:[1,0]
	v_pk_mul_f32 v[182:183], v[182:183], s[82:83] op_sel_hi:[1,0]
	v_pk_fma_f32 v[138:139], v[138:139], 0.5, v[180:181] op_sel_hi:[1,0,1]
	v_pk_fma_f32 v[140:141], v[140:141], 0.5, v[182:183] op_sel_hi:[1,0,1]
	s_nop 0
	global_store_dwordx4 v112, v[138:141], s[58:59] sc1
	global_load_dwordx4 v[180:183], v130, s[60:61]
	s_waitcnt vmcnt(4)
	v_pk_mul_f32 v[184:185], v[184:185], s[82:83] op_sel_hi:[1,0]
	v_pk_mul_f32 v[186:187], v[186:187], s[82:83] op_sel_hi:[1,0]
	v_pk_fma_f32 v[92:93], v[92:93], 0.5, v[184:185] op_sel_hi:[1,0,1]
	v_pk_fma_f32 v[94:95], v[94:95], 0.5, v[186:187] op_sel_hi:[1,0,1]
	s_nop 0
	global_store_dwordx4 v112, v[92:95], s[58:59] offset:64 sc1
	global_load_dwordx4 v[184:187], v130, s[60:61] offset:64
	s_waitcnt vmcnt(5)
	v_pk_mul_f32 v[188:189], v[188:189], s[82:83] op_sel_hi:[1,0]
	v_pk_mul_f32 v[190:191], v[190:191], s[82:83] op_sel_hi:[1,0]
	v_pk_fma_f32 v[126:127], v[126:127], 0.5, v[188:189] op_sel_hi:[1,0,1]
	v_pk_fma_f32 v[128:129], v[128:129], 0.5, v[190:191] op_sel_hi:[1,0,1]
	s_nop 0
	global_store_dwordx4 v113, v[126:129], s[58:59] sc1
	global_load_dwordx4 v[188:191], v131, s[60:61]
	s_waitcnt vmcnt(6)
	v_pk_mul_f32 v[192:193], v[192:193], s[82:83] op_sel_hi:[1,0]
	v_pk_mul_f32 v[194:195], v[194:195], s[82:83] op_sel_hi:[1,0]
	v_pk_fma_f32 v[88:89], v[88:89], 0.5, v[192:193] op_sel_hi:[1,0,1]
	v_pk_fma_f32 v[90:91], v[90:91], 0.5, v[194:195] op_sel_hi:[1,0,1]
	s_nop 0
	global_store_dwordx4 v113, v[88:91], s[58:59] offset:64 sc1
	global_load_dwordx4 v[192:195], v131, s[60:61] offset:64
	s_waitcnt vmcnt(6)
	v_pk_mul_f32 v[180:181], v[180:181], s[82:83] op_sel_hi:[1,0]
	v_pk_mul_f32 v[182:183], v[182:183], s[82:83] op_sel_hi:[1,0]
	v_pk_fma_f32 v[122:123], v[122:123], 0.5, v[180:181] op_sel_hi:[1,0,1]
	v_pk_fma_f32 v[124:125], v[124:125], 0.5, v[182:183] op_sel_hi:[1,0,1]
	s_nop 0
	global_store_dwordx4 v130, v[122:125], s[58:59] sc1
	global_load_dwordx4 v[180:183], v132, s[60:61]
	s_waitcnt vmcnt(6)
	v_pk_mul_f32 v[184:185], v[184:185], s[82:83] op_sel_hi:[1,0]
	v_pk_mul_f32 v[186:187], v[186:187], s[82:83] op_sel_hi:[1,0]
	v_pk_fma_f32 v[84:85], v[84:85], 0.5, v[184:185] op_sel_hi:[1,0,1]
	v_pk_fma_f32 v[86:87], v[86:87], 0.5, v[186:187] op_sel_hi:[1,0,1]
	s_nop 0
	global_store_dwordx4 v130, v[84:87], s[58:59] offset:64 sc1
	global_load_dwordx4 v[184:187], v132, s[60:61] offset:64
	s_waitcnt vmcnt(6)
	v_pk_mul_f32 v[188:189], v[188:189], s[82:83] op_sel_hi:[1,0]
	v_pk_mul_f32 v[190:191], v[190:191], s[82:83] op_sel_hi:[1,0]
	v_pk_fma_f32 v[118:119], v[118:119], 0.5, v[188:189] op_sel_hi:[1,0,1]
	v_pk_fma_f32 v[120:121], v[120:121], 0.5, v[190:191] op_sel_hi:[1,0,1]
	s_nop 0
	global_store_dwordx4 v131, v[118:121], s[58:59] sc1
	global_load_dwordx4 v[188:191], v133, s[60:61]
	s_waitcnt vmcnt(6)
	v_pk_mul_f32 v[192:193], v[192:193], s[82:83] op_sel_hi:[1,0]
	v_pk_mul_f32 v[194:195], v[194:195], s[82:83] op_sel_hi:[1,0]
	v_pk_fma_f32 v[80:81], v[80:81], 0.5, v[192:193] op_sel_hi:[1,0,1]
	v_pk_fma_f32 v[82:83], v[82:83], 0.5, v[194:195] op_sel_hi:[1,0,1]
	s_nop 0
	global_store_dwordx4 v131, v[80:83], s[58:59] offset:64 sc1
	global_load_dwordx4 v[192:195], v133, s[60:61] offset:64
	s_waitcnt vmcnt(6)
	v_pk_mul_f32 v[180:181], v[180:181], s[82:83] op_sel_hi:[1,0]
	v_pk_mul_f32 v[182:183], v[182:183], s[82:83] op_sel_hi:[1,0]
	v_pk_fma_f32 v[114:115], v[114:115], 0.5, v[180:181] op_sel_hi:[1,0,1]
	v_pk_fma_f32 v[116:117], v[116:117], 0.5, v[182:183] op_sel_hi:[1,0,1]
	s_nop 0
	global_store_dwordx4 v132, v[114:117], s[58:59] sc1
	global_load_dwordx4 v[180:183], v134, s[60:61]
	s_waitcnt vmcnt(6)
	v_pk_mul_f32 v[184:185], v[184:185], s[82:83] op_sel_hi:[1,0]
	v_pk_mul_f32 v[186:187], v[186:187], s[82:83] op_sel_hi:[1,0]
	v_pk_fma_f32 v[76:77], v[76:77], 0.5, v[184:185] op_sel_hi:[1,0,1]
	v_pk_fma_f32 v[78:79], v[78:79], 0.5, v[186:187] op_sel_hi:[1,0,1]
	s_nop 0
	global_store_dwordx4 v132, v[76:79], s[58:59] offset:64 sc1
	global_load_dwordx4 v[184:187], v134, s[60:61] offset:64
	s_waitcnt vmcnt(6)
	v_pk_mul_f32 v[188:189], v[188:189], s[82:83] op_sel_hi:[1,0]
	v_pk_mul_f32 v[190:191], v[190:191], s[82:83] op_sel_hi:[1,0]
	v_pk_fma_f32 v[104:105], v[104:105], 0.5, v[188:189] op_sel_hi:[1,0,1]
	v_pk_fma_f32 v[106:107], v[106:107], 0.5, v[190:191] op_sel_hi:[1,0,1]
	s_nop 0
	global_store_dwordx4 v133, v[104:107], s[58:59] sc1
	global_load_dwordx4 v[188:191], v135, s[60:61]
	s_waitcnt vmcnt(6)
	v_pk_mul_f32 v[192:193], v[192:193], s[82:83] op_sel_hi:[1,0]
	v_pk_mul_f32 v[194:195], v[194:195], s[82:83] op_sel_hi:[1,0]
	v_pk_fma_f32 v[72:73], v[72:73], 0.5, v[192:193] op_sel_hi:[1,0,1]
	v_pk_fma_f32 v[74:75], v[74:75], 0.5, v[194:195] op_sel_hi:[1,0,1]
	s_nop 0
	global_store_dwordx4 v133, v[72:75], s[58:59] offset:64 sc1
	global_load_dwordx4 v[192:195], v135, s[60:61] offset:64
	s_waitcnt vmcnt(6)
	v_pk_mul_f32 v[180:181], v[180:181], s[82:83] op_sel_hi:[1,0]
	v_pk_mul_f32 v[182:183], v[182:183], s[82:83] op_sel_hi:[1,0]
	v_pk_fma_f32 v[100:101], v[100:101], 0.5, v[180:181] op_sel_hi:[1,0,1]
	v_pk_fma_f32 v[102:103], v[102:103], 0.5, v[182:183] op_sel_hi:[1,0,1]
	s_nop 0
	global_store_dwordx4 v134, v[100:103], s[58:59] sc1
	global_load_dwordx4 v[180:183], v112, s[60:61] offset:512
	s_waitcnt vmcnt(6)
	v_pk_mul_f32 v[184:185], v[184:185], s[82:83] op_sel_hi:[1,0]
	v_pk_mul_f32 v[186:187], v[186:187], s[82:83] op_sel_hi:[1,0]
	v_pk_fma_f32 v[68:69], v[68:69], 0.5, v[184:185] op_sel_hi:[1,0,1]
	v_pk_fma_f32 v[70:71], v[70:71], 0.5, v[186:187] op_sel_hi:[1,0,1]
	s_nop 0
	global_store_dwordx4 v134, v[68:71], s[58:59] offset:64 sc1
	global_load_dwordx4 v[184:187], v112, s[60:61] offset:576
	s_waitcnt vmcnt(6)
	v_pk_mul_f32 v[188:189], v[188:189], s[82:83] op_sel_hi:[1,0]
	v_pk_mul_f32 v[190:191], v[190:191], s[82:83] op_sel_hi:[1,0]
	v_pk_fma_f32 v[96:97], v[96:97], 0.5, v[188:189] op_sel_hi:[1,0,1]
	v_pk_fma_f32 v[98:99], v[98:99], 0.5, v[190:191] op_sel_hi:[1,0,1]
	s_nop 0
	global_store_dwordx4 v135, v[96:99], s[58:59] sc1
	global_load_dwordx4 v[188:191], v113, s[60:61] offset:512
	s_waitcnt vmcnt(6)
	v_pk_mul_f32 v[192:193], v[192:193], s[82:83] op_sel_hi:[1,0]
	v_pk_mul_f32 v[194:195], v[194:195], s[82:83] op_sel_hi:[1,0]
	v_pk_fma_f32 v[64:65], v[64:65], 0.5, v[192:193] op_sel_hi:[1,0,1]
	v_pk_fma_f32 v[66:67], v[66:67], 0.5, v[194:195] op_sel_hi:[1,0,1]
	s_nop 0
	global_store_dwordx4 v135, v[64:67], s[58:59] offset:64 sc1
	global_load_dwordx4 v[192:195], v113, s[60:61] offset:576
	s_waitcnt vmcnt(6)
	v_pk_mul_f32 v[180:181], v[180:181], s[82:83] op_sel_hi:[1,0]
	v_pk_mul_f32 v[182:183], v[182:183], s[82:83] op_sel_hi:[1,0]
	v_pk_fma_f32 v[60:61], v[60:61], 0.5, v[180:181] op_sel_hi:[1,0,1]
	v_pk_fma_f32 v[62:63], v[62:63], 0.5, v[182:183] op_sel_hi:[1,0,1]
	s_nop 0
	global_store_dwordx4 v112, v[60:63], s[58:59] offset:512 sc1
	global_load_dwordx4 v[180:183], v130, s[60:61] offset:512
	s_waitcnt vmcnt(6)
	v_pk_mul_f32 v[184:185], v[184:185], s[82:83] op_sel_hi:[1,0]
	v_pk_mul_f32 v[186:187], v[186:187], s[82:83] op_sel_hi:[1,0]
	v_pk_fma_f32 v[28:29], v[28:29], 0.5, v[184:185] op_sel_hi:[1,0,1]
	v_pk_fma_f32 v[30:31], v[30:31], 0.5, v[186:187] op_sel_hi:[1,0,1]
	s_nop 0
	global_store_dwordx4 v112, v[28:31], s[58:59] offset:576 sc1
	global_load_dwordx4 v[184:187], v130, s[60:61] offset:576
	s_waitcnt vmcnt(6)
	v_pk_mul_f32 v[188:189], v[188:189], s[82:83] op_sel_hi:[1,0]
	v_pk_mul_f32 v[190:191], v[190:191], s[82:83] op_sel_hi:[1,0]
	v_pk_fma_f32 v[56:57], v[56:57], 0.5, v[188:189] op_sel_hi:[1,0,1]
	v_pk_fma_f32 v[58:59], v[58:59], 0.5, v[190:191] op_sel_hi:[1,0,1]
	s_nop 0
	global_store_dwordx4 v113, v[56:59], s[58:59] offset:512 sc1
	global_load_dwordx4 v[188:191], v131, s[60:61] offset:512
	s_waitcnt vmcnt(6)
	v_pk_mul_f32 v[192:193], v[192:193], s[82:83] op_sel_hi:[1,0]
	v_pk_mul_f32 v[194:195], v[194:195], s[82:83] op_sel_hi:[1,0]
	v_pk_fma_f32 v[24:25], v[24:25], 0.5, v[192:193] op_sel_hi:[1,0,1]
	v_pk_fma_f32 v[26:27], v[26:27], 0.5, v[194:195] op_sel_hi:[1,0,1]
	s_nop 0
	global_store_dwordx4 v113, v[24:27], s[58:59] offset:576 sc1
	global_load_dwordx4 v[192:195], v131, s[60:61] offset:576
	s_waitcnt vmcnt(6)
	v_pk_mul_f32 v[180:181], v[180:181], s[82:83] op_sel_hi:[1,0]
	v_pk_mul_f32 v[182:183], v[182:183], s[82:83] op_sel_hi:[1,0]
	v_pk_fma_f32 v[52:53], v[52:53], 0.5, v[180:181] op_sel_hi:[1,0,1]
	v_pk_fma_f32 v[54:55], v[54:55], 0.5, v[182:183] op_sel_hi:[1,0,1]
	s_nop 0
	global_store_dwordx4 v130, v[52:55], s[58:59] offset:512 sc1
	global_load_dwordx4 v[180:183], v132, s[60:61] offset:512
	s_waitcnt vmcnt(6)
	v_pk_mul_f32 v[184:185], v[184:185], s[82:83] op_sel_hi:[1,0]
	v_pk_mul_f32 v[186:187], v[186:187], s[82:83] op_sel_hi:[1,0]
	v_pk_fma_f32 v[20:21], v[20:21], 0.5, v[184:185] op_sel_hi:[1,0,1]
	v_pk_fma_f32 v[22:23], v[22:23], 0.5, v[186:187] op_sel_hi:[1,0,1]
	s_nop 0
	global_store_dwordx4 v130, v[20:23], s[58:59] offset:576 sc1
	global_load_dwordx4 v[184:187], v132, s[60:61] offset:576
	s_waitcnt vmcnt(6)
	v_pk_mul_f32 v[188:189], v[188:189], s[82:83] op_sel_hi:[1,0]
	v_pk_mul_f32 v[190:191], v[190:191], s[82:83] op_sel_hi:[1,0]
	v_pk_fma_f32 v[48:49], v[48:49], 0.5, v[188:189] op_sel_hi:[1,0,1]
	v_pk_fma_f32 v[50:51], v[50:51], 0.5, v[190:191] op_sel_hi:[1,0,1]
	s_nop 0
	global_store_dwordx4 v131, v[48:51], s[58:59] offset:512 sc1
	global_load_dwordx4 v[188:191], v133, s[60:61] offset:512
	s_waitcnt vmcnt(6)
	v_pk_mul_f32 v[192:193], v[192:193], s[82:83] op_sel_hi:[1,0]
	v_pk_mul_f32 v[194:195], v[194:195], s[82:83] op_sel_hi:[1,0]
	v_pk_fma_f32 v[16:17], v[16:17], 0.5, v[192:193] op_sel_hi:[1,0,1]
	v_pk_fma_f32 v[18:19], v[18:19], 0.5, v[194:195] op_sel_hi:[1,0,1]
	s_nop 0
	global_store_dwordx4 v131, v[16:19], s[58:59] offset:576 sc1
	global_load_dwordx4 v[192:195], v133, s[60:61] offset:576
	s_waitcnt vmcnt(6)
	v_pk_mul_f32 v[180:181], v[180:181], s[82:83] op_sel_hi:[1,0]
	v_pk_mul_f32 v[182:183], v[182:183], s[82:83] op_sel_hi:[1,0]
	v_pk_fma_f32 v[44:45], v[44:45], 0.5, v[180:181] op_sel_hi:[1,0,1]
	v_pk_fma_f32 v[46:47], v[46:47], 0.5, v[182:183] op_sel_hi:[1,0,1]
	s_nop 0
	global_store_dwordx4 v132, v[44:47], s[58:59] offset:512 sc1
	global_load_dwordx4 v[180:183], v134, s[60:61] offset:512
	s_waitcnt vmcnt(6)
	v_pk_mul_f32 v[184:185], v[184:185], s[82:83] op_sel_hi:[1,0]
	v_pk_mul_f32 v[186:187], v[186:187], s[82:83] op_sel_hi:[1,0]
	v_pk_fma_f32 v[12:13], v[12:13], 0.5, v[184:185] op_sel_hi:[1,0,1]
	v_pk_fma_f32 v[14:15], v[14:15], 0.5, v[186:187] op_sel_hi:[1,0,1]
	s_nop 0
	global_store_dwordx4 v132, v[12:15], s[58:59] offset:576 sc1
	global_load_dwordx4 v[184:187], v134, s[60:61] offset:576
	s_waitcnt vmcnt(6)
	v_pk_mul_f32 v[188:189], v[188:189], s[82:83] op_sel_hi:[1,0]
	v_pk_mul_f32 v[190:191], v[190:191], s[82:83] op_sel_hi:[1,0]
	v_pk_fma_f32 v[40:41], v[40:41], 0.5, v[188:189] op_sel_hi:[1,0,1]
	v_pk_fma_f32 v[42:43], v[42:43], 0.5, v[190:191] op_sel_hi:[1,0,1]
	s_nop 0
	global_store_dwordx4 v133, v[40:43], s[58:59] offset:512 sc1
	global_load_dwordx4 v[188:191], v135, s[60:61] offset:512
	s_waitcnt vmcnt(6)
	v_pk_mul_f32 v[192:193], v[192:193], s[82:83] op_sel_hi:[1,0]
	v_pk_mul_f32 v[194:195], v[194:195], s[82:83] op_sel_hi:[1,0]
	v_pk_fma_f32 v[8:9], v[8:9], 0.5, v[192:193] op_sel_hi:[1,0,1]
	v_pk_fma_f32 v[10:11], v[10:11], 0.5, v[194:195] op_sel_hi:[1,0,1]
	s_nop 0
	global_store_dwordx4 v133, v[8:11], s[58:59] offset:576 sc1
	global_load_dwordx4 v[192:195], v135, s[60:61] offset:576
	s_waitcnt vmcnt(6)
	v_pk_mul_f32 v[180:181], v[180:181], s[82:83] op_sel_hi:[1,0]
	v_pk_mul_f32 v[182:183], v[182:183], s[82:83] op_sel_hi:[1,0]
	v_pk_fma_f32 v[36:37], v[36:37], 0.5, v[180:181] op_sel_hi:[1,0,1]
	v_pk_fma_f32 v[38:39], v[38:39], 0.5, v[182:183] op_sel_hi:[1,0,1]
	s_nop 0
	global_store_dwordx4 v134, v[36:39], s[58:59] offset:512 sc1
	s_waitcnt vmcnt(5)
	v_pk_mul_f32 v[184:185], v[184:185], s[82:83] op_sel_hi:[1,0]
	v_pk_mul_f32 v[186:187], v[186:187], s[82:83] op_sel_hi:[1,0]
	v_pk_fma_f32 v[4:5], v[4:5], 0.5, v[184:185] op_sel_hi:[1,0,1]
	v_pk_fma_f32 v[6:7], v[6:7], 0.5, v[186:187] op_sel_hi:[1,0,1]
	s_nop 0
	global_store_dwordx4 v134, v[4:7], s[58:59] offset:576 sc1
	s_waitcnt vmcnt(4)
	v_pk_mul_f32 v[188:189], v[188:189], s[82:83] op_sel_hi:[1,0]
	v_pk_mul_f32 v[190:191], v[190:191], s[82:83] op_sel_hi:[1,0]
	v_pk_fma_f32 v[32:33], v[32:33], 0.5, v[188:189] op_sel_hi:[1,0,1]
	v_pk_fma_f32 v[34:35], v[34:35], 0.5, v[190:191] op_sel_hi:[1,0,1]
	s_nop 0
	global_store_dwordx4 v135, v[32:35], s[58:59] offset:512 sc1
	s_waitcnt vmcnt(3)
	v_pk_mul_f32 v[192:193], v[192:193], s[82:83] op_sel_hi:[1,0]
	v_pk_mul_f32 v[194:195], v[194:195], s[82:83] op_sel_hi:[1,0]
	v_pk_fma_f32 v[0:1], v[0:1], 0.5, v[192:193] op_sel_hi:[1,0,1]
	v_pk_fma_f32 v[2:3], v[2:3], 0.5, v[194:195] op_sel_hi:[1,0,1]
	s_nop 0
	global_store_dwordx4 v135, v[0:3], s[58:59] offset:576 sc1

.LBB0_1086:
	v_lshl_add_u32 v248, s60, 8, v138
	v_lshl_or_b32 v249, s75, 8, v139
	v_lshlrev_b32_e32 v248, 3, v248
	v_lshlrev_b32_e32 v249, 2, v249
	s_ashr_i32 s61, s60, 31
	s_lshl_b64 s[28:29], s[60:61], 20
	v_readlane_b32 s4, v252, 0
	v_readlane_b32 s5, v252, 1
	v_readlane_b32 s6, v252, 2
	v_readlane_b32 s7, v252, 3
	v_readlane_b32 s8, v252, 4
	v_readlane_b32 s9, v252, 5
	v_readlane_b32 s10, v252, 6
	v_readlane_b32 s11, v252, 7
	v_readlane_b32 s12, v252, 8
	v_readlane_b32 s13, v252, 9
	v_readlane_b32 s14, v252, 10
	v_readlane_b32 s15, v252, 11
	v_readlane_b32 s16, v252, 12
	v_readlane_b32 s17, v252, 13
	s_mov_b64 s[4:5], s[8:9]
	v_readlane_b32 s18, v252, 14
	v_readlane_b32 s19, v252, 15
	s_mov_b64 s[6:7], s[10:11]
	s_mov_b64 s[8:9], s[12:13]
	s_mov_b64 s[12:13], s[16:17]
	s_add_u32 s60, s12, s28
	s_addc_u32 s61, s13, s29
	s_mov_b64 s[14:15], s[18:19]
	global_load_dwordx2 v[208:209], v248, s[92:93]
	global_load_dwordx2 v[210:211], v248, s[92:93] offset:128
	global_load_dwordx2 v[212:213], v248, s[92:93] offset:256
	global_load_dwordx2 v[214:215], v248, s[92:93] offset:384
	global_load_dwordx2 v[216:217], v248, s[92:93] offset:1024
	global_load_dwordx2 v[218:219], v248, s[92:93] offset:1152
	global_load_dwordx2 v[220:221], v248, s[92:93] offset:1280
	global_load_dwordx2 v[230:231], v248, s[92:93] offset:1408
	global_load_dwordx4 v[190:193], v249, s[44:45]
	global_load_dwordx4 v[194:197], v249, s[46:47]
	global_load_dwordx4 v[200:203], v249, s[44:45] offset:64
	global_load_dwordx4 v[204:207], v249, s[46:47] offset:64
	global_load_dwordx4 v[232:235], v249, s[44:45] offset:512
	global_load_dwordx4 v[236:239], v249, s[46:47] offset:512
	global_load_dwordx4 v[240:243], v249, s[44:45] offset:576
	global_load_dwordx4 v[244:247], v249, s[46:47] offset:576
	v_add_u32_e32 v124, v140, v249
	v_add_u32_e32 v125, v164, v249
	v_add_u32_e32 v126, v166, v249
	v_add_u32_e32 v127, v168, v249
	v_add_u32_e32 v128, v156, v249
	v_add_u32_e32 v129, v158, v249
	v_add_u32_e32 v130, v160, v249
	v_add_u32_e32 v131, v162, v249
	global_load_dwordx4 v[174:177], v124, s[60:61]
	global_load_dwordx4 v[178:181], v124, s[60:61] offset:64
	global_load_dwordx4 v[182:185], v125, s[60:61]
	global_load_dwordx4 v[186:189], v125, s[60:61] offset:64
	s_waitcnt vmcnt(3)
	v_pk_add_f32 v[174:175], v[174:175], v[208:209] op_sel_hi:[1,0] neg_lo:[0,1] neg_hi:[0,1]
	v_pk_add_f32 v[176:177], v[176:177], v[208:209] op_sel_hi:[1,0] neg_lo:[0,1] neg_hi:[0,1]
	v_pk_mul_f32 v[174:175], v[174:175], v[208:209] op_sel:[0,1] op_sel_hi:[1,1]
	v_pk_mul_f32 v[176:177], v[176:177], v[208:209] op_sel:[0,1] op_sel_hi:[1,1]
	v_pk_fma_f32 v[174:175], v[190:191], v[174:175], v[194:195]
	v_pk_fma_f32 v[176:177], v[192:193], v[176:177], v[196:197]
	v_pk_fma_f32 v[132:133], v[174:175], s[82:83], v[132:133] op_sel_hi:[1,0,1]
	v_pk_fma_f32 v[134:135], v[176:177], s[82:83], v[134:135] op_sel_hi:[1,0,1]
	s_nop 0
	global_store_dwordx4 v124, v[132:135], s[60:61] sc1
	global_load_dwordx4 v[174:177], v126, s[60:61]
	s_waitcnt vmcnt(4)
	v_pk_add_f32 v[178:179], v[178:179], v[208:209] op_sel_hi:[1,0] neg_lo:[0,1] neg_hi:[0,1]
	v_pk_add_f32 v[180:181], v[180:181], v[208:209] op_sel_hi:[1,0] neg_lo:[0,1] neg_hi:[0,1]
	v_pk_mul_f32 v[178:179], v[178:179], v[208:209] op_sel:[0,1] op_sel_hi:[1,1]
	v_pk_mul_f32 v[180:181], v[180:181], v[208:209] op_sel:[0,1] op_sel_hi:[1,1]
	v_pk_fma_f32 v[178:179], v[200:201], v[178:179], v[204:205]
	v_pk_fma_f32 v[180:181], v[202:203], v[180:181], v[206:207]
	v_pk_fma_f32 v[96:97], v[178:179], s[82:83], v[96:97] op_sel_hi:[1,0,1]
	v_pk_fma_f32 v[98:99], v[180:181], s[82:83], v[98:99] op_sel_hi:[1,0,1]
	s_nop 0
	global_store_dwordx4 v124, v[96:99], s[60:61] offset:64 sc1
	global_load_dwordx4 v[178:181], v126, s[60:61] offset:64
	s_waitcnt vmcnt(5)
	v_pk_add_f32 v[182:183], v[182:183], v[210:211] op_sel_hi:[1,0] neg_lo:[0,1] neg_hi:[0,1]
	v_pk_add_f32 v[184:185], v[184:185], v[210:211] op_sel_hi:[1,0] neg_lo:[0,1] neg_hi:[0,1]
	v_pk_mul_f32 v[182:183], v[182:183], v[210:211] op_sel:[0,1] op_sel_hi:[1,1]
	v_pk_mul_f32 v[184:185], v[184:185], v[210:211] op_sel:[0,1] op_sel_hi:[1,1]
	v_pk_fma_f32 v[182:183], v[190:191], v[182:183], v[194:195]
	v_pk_fma_f32 v[184:185], v[192:193], v[184:185], v[196:197]
	v_pk_fma_f32 v[120:121], v[182:183], s[82:83], v[120:121] op_sel_hi:[1,0,1]
	v_pk_fma_f32 v[122:123], v[184:185], s[82:83], v[122:123] op_sel_hi:[1,0,1]
	s_nop 0
	global_store_dwordx4 v125, v[120:123], s[60:61] sc1
	global_load_dwordx4 v[182:185], v127, s[60:61]
	s_waitcnt vmcnt(6)
	v_pk_add_f32 v[186:187], v[186:187], v[210:211] op_sel_hi:[1,0] neg_lo:[0,1] neg_hi:[0,1]
	v_pk_add_f32 v[188:189], v[188:189], v[210:211] op_sel_hi:[1,0] neg_lo:[0,1] neg_hi:[0,1]
	v_pk_mul_f32 v[186:187], v[186:187], v[210:211] op_sel:[0,1] op_sel_hi:[1,1]
	v_pk_mul_f32 v[188:189], v[188:189], v[210:211] op_sel:[0,1] op_sel_hi:[1,1]
	v_pk_fma_f32 v[186:187], v[200:201], v[186:187], v[204:205]
	v_pk_fma_f32 v[188:189], v[202:203], v[188:189], v[206:207]
	v_pk_fma_f32 v[88:89], v[186:187], s[82:83], v[88:89] op_sel_hi:[1,0,1]
	v_pk_fma_f32 v[90:91], v[188:189], s[82:83], v[90:91] op_sel_hi:[1,0,1]
	s_nop 0
	global_store_dwordx4 v125, v[88:91], s[60:61] offset:64 sc1
	global_load_dwordx4 v[186:189], v127, s[60:61] offset:64
	s_waitcnt vmcnt(6)
	v_pk_add_f32 v[174:175], v[174:175], v[212:213] op_sel_hi:[1,0] neg_lo:[0,1] neg_hi:[0,1]
	v_pk_add_f32 v[176:177], v[176:177], v[212:213] op_sel_hi:[1,0] neg_lo:[0,1] neg_hi:[0,1]
	v_pk_mul_f32 v[174:175], v[174:175], v[212:213] op_sel:[0,1] op_sel_hi:[1,1]
	v_pk_mul_f32 v[176:177], v[176:177], v[212:213] op_sel:[0,1] op_sel_hi:[1,1]
	v_pk_fma_f32 v[174:175], v[190:191], v[174:175], v[194:195]
	v_pk_fma_f32 v[176:177], v[192:193], v[176:177], v[196:197]
	v_pk_fma_f32 v[116:117], v[174:175], s[82:83], v[116:117] op_sel_hi:[1,0,1]
	v_pk_fma_f32 v[118:119], v[176:177], s[82:83], v[118:119] op_sel_hi:[1,0,1]
	s_nop 0
	global_store_dwordx4 v126, v[116:119], s[60:61] sc1
	global_load_dwordx4 v[174:177], v128, s[60:61]
	s_waitcnt vmcnt(6)
	v_pk_add_f32 v[178:179], v[178:179], v[212:213] op_sel_hi:[1,0] neg_lo:[0,1] neg_hi:[0,1]
	v_pk_add_f32 v[180:181], v[180:181], v[212:213] op_sel_hi:[1,0] neg_lo:[0,1] neg_hi:[0,1]
	v_pk_mul_f32 v[178:179], v[178:179], v[212:213] op_sel:[0,1] op_sel_hi:[1,1]
	v_pk_mul_f32 v[180:181], v[180:181], v[212:213] op_sel:[0,1] op_sel_hi:[1,1]
	v_pk_fma_f32 v[178:179], v[200:201], v[178:179], v[204:205]
	v_pk_fma_f32 v[180:181], v[202:203], v[180:181], v[206:207]
	v_pk_fma_f32 v[84:85], v[178:179], s[82:83], v[84:85] op_sel_hi:[1,0,1]
	v_pk_fma_f32 v[86:87], v[180:181], s[82:83], v[86:87] op_sel_hi:[1,0,1]
	s_nop 0
	global_store_dwordx4 v126, v[84:87], s[60:61] offset:64 sc1
	global_load_dwordx4 v[178:181], v128, s[60:61] offset:64
	s_waitcnt vmcnt(6)
	v_pk_add_f32 v[182:183], v[182:183], v[214:215] op_sel_hi:[1,0] neg_lo:[0,1] neg_hi:[0,1]
	v_pk_add_f32 v[184:185], v[184:185], v[214:215] op_sel_hi:[1,0] neg_lo:[0,1] neg_hi:[0,1]
	v_pk_mul_f32 v[182:183], v[182:183], v[214:215] op_sel:[0,1] op_sel_hi:[1,1]
	v_pk_mul_f32 v[184:185], v[184:185], v[214:215] op_sel:[0,1] op_sel_hi:[1,1]
	v_pk_fma_f32 v[182:183], v[190:191], v[182:183], v[194:195]
	v_pk_fma_f32 v[184:185], v[192:193], v[184:185], v[196:197]
	v_pk_fma_f32 v[112:113], v[182:183], s[82:83], v[112:113] op_sel_hi:[1,0,1]
	v_pk_fma_f32 v[114:115], v[184:185], s[82:83], v[114:115] op_sel_hi:[1,0,1]
	s_nop 0
	global_store_dwordx4 v127, v[112:115], s[60:61] sc1
	global_load_dwordx4 v[182:185], v129, s[60:61]
	s_waitcnt vmcnt(6)
	v_pk_add_f32 v[186:187], v[186:187], v[214:215] op_sel_hi:[1,0] neg_lo:[0,1] neg_hi:[0,1]
	v_pk_add_f32 v[188:189], v[188:189], v[214:215] op_sel_hi:[1,0] neg_lo:[0,1] neg_hi:[0,1]
	v_pk_mul_f32 v[186:187], v[186:187], v[214:215] op_sel:[0,1] op_sel_hi:[1,1]
	v_pk_mul_f32 v[188:189], v[188:189], v[214:215] op_sel:[0,1] op_sel_hi:[1,1]
	v_pk_fma_f32 v[186:187], v[200:201], v[186:187], v[204:205]
	v_pk_fma_f32 v[188:189], v[202:203], v[188:189], v[206:207]
	v_pk_fma_f32 v[80:81], v[186:187], s[82:83], v[80:81] op_sel_hi:[1,0,1]
	v_pk_fma_f32 v[82:83], v[188:189], s[82:83], v[82:83] op_sel_hi:[1,0,1]
	s_nop 0
	global_store_dwordx4 v127, v[80:83], s[60:61] offset:64 sc1
	global_load_dwordx4 v[186:189], v129, s[60:61] offset:64
	s_waitcnt vmcnt(6)
	v_pk_add_f32 v[174:175], v[174:175], v[216:217] op_sel_hi:[1,0] neg_lo:[0,1] neg_hi:[0,1]
	v_pk_add_f32 v[176:177], v[176:177], v[216:217] op_sel_hi:[1,0] neg_lo:[0,1] neg_hi:[0,1]
	v_pk_mul_f32 v[174:175], v[174:175], v[216:217] op_sel:[0,1] op_sel_hi:[1,1]
	v_pk_mul_f32 v[176:177], v[176:177], v[216:217] op_sel:[0,1] op_sel_hi:[1,1]
	v_pk_fma_f32 v[174:175], v[190:191], v[174:175], v[194:195]
	v_pk_fma_f32 v[176:177], v[192:193], v[176:177], v[196:197]
	v_pk_fma_f32 v[108:109], v[174:175], s[82:83], v[108:109] op_sel_hi:[1,0,1]
	v_pk_fma_f32 v[110:111], v[176:177], s[82:83], v[110:111] op_sel_hi:[1,0,1]
	s_nop 0
	global_store_dwordx4 v128, v[108:111], s[60:61] sc1
	global_load_dwordx4 v[174:177], v130, s[60:61]
	s_waitcnt vmcnt(6)
	v_pk_add_f32 v[178:179], v[178:179], v[216:217] op_sel_hi:[1,0] neg_lo:[0,1] neg_hi:[0,1]
	v_pk_add_f32 v[180:181], v[180:181], v[216:217] op_sel_hi:[1,0] neg_lo:[0,1] neg_hi:[0,1]
	v_pk_mul_f32 v[178:179], v[178:179], v[216:217] op_sel:[0,1] op_sel_hi:[1,1]
	v_pk_mul_f32 v[180:181], v[180:181], v[216:217] op_sel:[0,1] op_sel_hi:[1,1]
	v_pk_fma_f32 v[178:179], v[200:201], v[178:179], v[204:205]
	v_pk_fma_f32 v[180:181], v[202:203], v[180:181], v[206:207]
	v_pk_fma_f32 v[76:77], v[178:179], s[82:83], v[76:77] op_sel_hi:[1,0,1]
	v_pk_fma_f32 v[78:79], v[180:181], s[82:83], v[78:79] op_sel_hi:[1,0,1]
	s_nop 0
	global_store_dwordx4 v128, v[76:79], s[60:61] offset:64 sc1
	global_load_dwordx4 v[178:181], v130, s[60:61] offset:64
	s_waitcnt vmcnt(6)
	v_pk_add_f32 v[182:183], v[182:183], v[218:219] op_sel_hi:[1,0] neg_lo:[0,1] neg_hi:[0,1]
	v_pk_add_f32 v[184:185], v[184:185], v[218:219] op_sel_hi:[1,0] neg_lo:[0,1] neg_hi:[0,1]
	v_pk_mul_f32 v[182:183], v[182:183], v[218:219] op_sel:[0,1] op_sel_hi:[1,1]
	v_pk_mul_f32 v[184:185], v[184:185], v[218:219] op_sel:[0,1] op_sel_hi:[1,1]
	v_pk_fma_f32 v[182:183], v[190:191], v[182:183], v[194:195]
	v_pk_fma_f32 v[184:185], v[192:193], v[184:185], v[196:197]
	v_pk_fma_f32 v[104:105], v[182:183], s[82:83], v[104:105] op_sel_hi:[1,0,1]
	v_pk_fma_f32 v[106:107], v[184:185], s[82:83], v[106:107] op_sel_hi:[1,0,1]
	s_nop 0
	global_store_dwordx4 v129, v[104:107], s[60:61] sc1
	global_load_dwordx4 v[182:185], v131, s[60:61]
	s_waitcnt vmcnt(6)
	v_pk_add_f32 v[186:187], v[186:187], v[218:219] op_sel_hi:[1,0] neg_lo:[0,1] neg_hi:[0,1]
	v_pk_add_f32 v[188:189], v[188:189], v[218:219] op_sel_hi:[1,0] neg_lo:[0,1] neg_hi:[0,1]
	v_pk_mul_f32 v[186:187], v[186:187], v[218:219] op_sel:[0,1] op_sel_hi:[1,1]
	v_pk_mul_f32 v[188:189], v[188:189], v[218:219] op_sel:[0,1] op_sel_hi:[1,1]
	v_pk_fma_f32 v[186:187], v[200:201], v[186:187], v[204:205]
	v_pk_fma_f32 v[188:189], v[202:203], v[188:189], v[206:207]
	v_pk_fma_f32 v[72:73], v[186:187], s[82:83], v[72:73] op_sel_hi:[1,0,1]
	v_pk_fma_f32 v[74:75], v[188:189], s[82:83], v[74:75] op_sel_hi:[1,0,1]
	s_nop 0
	global_store_dwordx4 v129, v[72:75], s[60:61] offset:64 sc1
	global_load_dwordx4 v[186:189], v131, s[60:61] offset:64
	s_waitcnt vmcnt(6)
	v_pk_add_f32 v[174:175], v[174:175], v[220:221] op_sel_hi:[1,0] neg_lo:[0,1] neg_hi:[0,1]
	v_pk_add_f32 v[176:177], v[176:177], v[220:221] op_sel_hi:[1,0] neg_lo:[0,1] neg_hi:[0,1]
	v_pk_mul_f32 v[174:175], v[174:175], v[220:221] op_sel:[0,1] op_sel_hi:[1,1]
	v_pk_mul_f32 v[176:177], v[176:177], v[220:221] op_sel:[0,1] op_sel_hi:[1,1]
	v_pk_fma_f32 v[174:175], v[190:191], v[174:175], v[194:195]
	v_pk_fma_f32 v[176:177], v[192:193], v[176:177], v[196:197]
	v_pk_fma_f32 v[100:101], v[174:175], s[82:83], v[100:101] op_sel_hi:[1,0,1]
	v_pk_fma_f32 v[102:103], v[176:177], s[82:83], v[102:103] op_sel_hi:[1,0,1]
	s_nop 0
	global_store_dwordx4 v130, v[100:103], s[60:61] sc1
	global_load_dwordx4 v[174:177], v124, s[60:61] offset:512
	s_waitcnt vmcnt(6)
	v_pk_add_f32 v[178:179], v[178:179], v[220:221] op_sel_hi:[1,0] neg_lo:[0,1] neg_hi:[0,1]
	v_pk_add_f32 v[180:181], v[180:181], v[220:221] op_sel_hi:[1,0] neg_lo:[0,1] neg_hi:[0,1]
	v_pk_mul_f32 v[178:179], v[178:179], v[220:221] op_sel:[0,1] op_sel_hi:[1,1]
	v_pk_mul_f32 v[180:181], v[180:181], v[220:221] op_sel:[0,1] op_sel_hi:[1,1]
	v_pk_fma_f32 v[178:179], v[200:201], v[178:179], v[204:205]
	v_pk_fma_f32 v[180:181], v[202:203], v[180:181], v[206:207]
	v_pk_fma_f32 v[68:69], v[178:179], s[82:83], v[68:69] op_sel_hi:[1,0,1]
	v_pk_fma_f32 v[70:71], v[180:181], s[82:83], v[70:71] op_sel_hi:[1,0,1]
	s_nop 0
	global_store_dwordx4 v130, v[68:71], s[60:61] offset:64 sc1
	global_load_dwordx4 v[178:181], v124, s[60:61] offset:576
	s_waitcnt vmcnt(6)
	v_pk_add_f32 v[182:183], v[182:183], v[230:231] op_sel_hi:[1,0] neg_lo:[0,1] neg_hi:[0,1]
	v_pk_add_f32 v[184:185], v[184:185], v[230:231] op_sel_hi:[1,0] neg_lo:[0,1] neg_hi:[0,1]
	v_pk_mul_f32 v[182:183], v[182:183], v[230:231] op_sel:[0,1] op_sel_hi:[1,1]
	v_pk_mul_f32 v[184:185], v[184:185], v[230:231] op_sel:[0,1] op_sel_hi:[1,1]
	v_pk_fma_f32 v[182:183], v[190:191], v[182:183], v[194:195]
	v_pk_fma_f32 v[184:185], v[192:193], v[184:185], v[196:197]
	v_pk_fma_f32 v[92:93], v[182:183], s[82:83], v[92:93] op_sel_hi:[1,0,1]
	v_pk_fma_f32 v[94:95], v[184:185], s[82:83], v[94:95] op_sel_hi:[1,0,1]
	s_nop 0
	global_store_dwordx4 v131, v[92:95], s[60:61] sc1
	global_load_dwordx4 v[182:185], v125, s[60:61] offset:512
	s_waitcnt vmcnt(6)
	v_pk_add_f32 v[186:187], v[186:187], v[230:231] op_sel_hi:[1,0] neg_lo:[0,1] neg_hi:[0,1]
	v_pk_add_f32 v[188:189], v[188:189], v[230:231] op_sel_hi:[1,0] neg_lo:[0,1] neg_hi:[0,1]
	v_pk_mul_f32 v[186:187], v[186:187], v[230:231] op_sel:[0,1] op_sel_hi:[1,1]
	v_pk_mul_f32 v[188:189], v[188:189], v[230:231] op_sel:[0,1] op_sel_hi:[1,1]
	v_pk_fma_f32 v[186:187], v[200:201], v[186:187], v[204:205]
	v_pk_fma_f32 v[188:189], v[202:203], v[188:189], v[206:207]
	v_pk_fma_f32 v[60:61], v[186:187], s[82:83], v[60:61] op_sel_hi:[1,0,1]
	v_pk_fma_f32 v[62:63], v[188:189], s[82:83], v[62:63] op_sel_hi:[1,0,1]
	s_nop 0
	global_store_dwordx4 v131, v[60:63], s[60:61] offset:64 sc1
	global_load_dwordx4 v[186:189], v125, s[60:61] offset:576
	s_waitcnt vmcnt(6)
	v_pk_add_f32 v[174:175], v[174:175], v[208:209] op_sel_hi:[1,0] neg_lo:[0,1] neg_hi:[0,1]
	v_pk_add_f32 v[176:177], v[176:177], v[208:209] op_sel_hi:[1,0] neg_lo:[0,1] neg_hi:[0,1]
	v_pk_mul_f32 v[174:175], v[174:175], v[208:209] op_sel:[0,1] op_sel_hi:[1,1]
	v_pk_mul_f32 v[176:177], v[176:177], v[208:209] op_sel:[0,1] op_sel_hi:[1,1]
	v_pk_fma_f32 v[174:175], v[232:233], v[174:175], v[236:237]
	v_pk_fma_f32 v[176:177], v[234:235], v[176:177], v[238:239]
	v_pk_fma_f32 v[64:65], v[174:175], s[82:83], v[64:65] op_sel_hi:[1,0,1]
	v_pk_fma_f32 v[66:67], v[176:177], s[82:83], v[66:67] op_sel_hi:[1,0,1]
	s_nop 0
	global_store_dwordx4 v124, v[64:67], s[60:61] offset:512 sc1
	global_load_dwordx4 v[174:177], v126, s[60:61] offset:512
	s_waitcnt vmcnt(6)
	v_pk_add_f32 v[178:179], v[178:179], v[208:209] op_sel_hi:[1,0] neg_lo:[0,1] neg_hi:[0,1]
	v_pk_add_f32 v[180:181], v[180:181], v[208:209] op_sel_hi:[1,0] neg_lo:[0,1] neg_hi:[0,1]
	v_pk_mul_f32 v[178:179], v[178:179], v[208:209] op_sel:[0,1] op_sel_hi:[1,1]
	v_pk_mul_f32 v[180:181], v[180:181], v[208:209] op_sel:[0,1] op_sel_hi:[1,1]
	v_pk_fma_f32 v[178:179], v[240:241], v[178:179], v[244:245]
	v_pk_fma_f32 v[180:181], v[242:243], v[180:181], v[246:247]
	v_pk_fma_f32 v[32:33], v[178:179], s[82:83], v[32:33] op_sel_hi:[1,0,1]
	v_pk_fma_f32 v[34:35], v[180:181], s[82:83], v[34:35] op_sel_hi:[1,0,1]
	s_nop 0
	global_store_dwordx4 v124, v[32:35], s[60:61] offset:576 sc1
	global_load_dwordx4 v[178:181], v126, s[60:61] offset:576
	s_waitcnt vmcnt(6)
	v_pk_add_f32 v[182:183], v[182:183], v[210:211] op_sel_hi:[1,0] neg_lo:[0,1] neg_hi:[0,1]
	v_pk_add_f32 v[184:185], v[184:185], v[210:211] op_sel_hi:[1,0] neg_lo:[0,1] neg_hi:[0,1]
	v_pk_mul_f32 v[182:183], v[182:183], v[210:211] op_sel:[0,1] op_sel_hi:[1,1]
	v_pk_mul_f32 v[184:185], v[184:185], v[210:211] op_sel:[0,1] op_sel_hi:[1,1]
	v_pk_fma_f32 v[182:183], v[232:233], v[182:183], v[236:237]
	v_pk_fma_f32 v[184:185], v[234:235], v[184:185], v[238:239]
	v_pk_fma_f32 v[56:57], v[182:183], s[82:83], v[56:57] op_sel_hi:[1,0,1]
	v_pk_fma_f32 v[58:59], v[184:185], s[82:83], v[58:59] op_sel_hi:[1,0,1]
	s_nop 0
	global_store_dwordx4 v125, v[56:59], s[60:61] offset:512 sc1
	global_load_dwordx4 v[182:185], v127, s[60:61] offset:512
	s_waitcnt vmcnt(6)
	v_pk_add_f32 v[186:187], v[186:187], v[210:211] op_sel_hi:[1,0] neg_lo:[0,1] neg_hi:[0,1]
	v_pk_add_f32 v[188:189], v[188:189], v[210:211] op_sel_hi:[1,0] neg_lo:[0,1] neg_hi:[0,1]
	v_pk_mul_f32 v[186:187], v[186:187], v[210:211] op_sel:[0,1] op_sel_hi:[1,1]
	v_pk_mul_f32 v[188:189], v[188:189], v[210:211] op_sel:[0,1] op_sel_hi:[1,1]
	v_pk_fma_f32 v[186:187], v[240:241], v[186:187], v[244:245]
	v_pk_fma_f32 v[188:189], v[242:243], v[188:189], v[246:247]
	v_pk_fma_f32 v[24:25], v[186:187], s[82:83], v[24:25] op_sel_hi:[1,0,1]
	v_pk_fma_f32 v[26:27], v[188:189], s[82:83], v[26:27] op_sel_hi:[1,0,1]
	s_nop 0
	global_store_dwordx4 v125, v[24:27], s[60:61] offset:576 sc1
	global_load_dwordx4 v[186:189], v127, s[60:61] offset:576
	s_waitcnt vmcnt(6)
	v_pk_add_f32 v[174:175], v[174:175], v[212:213] op_sel_hi:[1,0] neg_lo:[0,1] neg_hi:[0,1]
	v_pk_add_f32 v[176:177], v[176:177], v[212:213] op_sel_hi:[1,0] neg_lo:[0,1] neg_hi:[0,1]
	v_pk_mul_f32 v[174:175], v[174:175], v[212:213] op_sel:[0,1] op_sel_hi:[1,1]
	v_pk_mul_f32 v[176:177], v[176:177], v[212:213] op_sel:[0,1] op_sel_hi:[1,1]
	v_pk_fma_f32 v[174:175], v[232:233], v[174:175], v[236:237]
	v_pk_fma_f32 v[176:177], v[234:235], v[176:177], v[238:239]
	v_pk_fma_f32 v[52:53], v[174:175], s[82:83], v[52:53] op_sel_hi:[1,0,1]
	v_pk_fma_f32 v[54:55], v[176:177], s[82:83], v[54:55] op_sel_hi:[1,0,1]
	s_nop 0
	global_store_dwordx4 v126, v[52:55], s[60:61] offset:512 sc1
	global_load_dwordx4 v[174:177], v128, s[60:61] offset:512
	s_waitcnt vmcnt(6)
	v_pk_add_f32 v[178:179], v[178:179], v[212:213] op_sel_hi:[1,0] neg_lo:[0,1] neg_hi:[0,1]
	v_pk_add_f32 v[180:181], v[180:181], v[212:213] op_sel_hi:[1,0] neg_lo:[0,1] neg_hi:[0,1]
	v_pk_mul_f32 v[178:179], v[178:179], v[212:213] op_sel:[0,1] op_sel_hi:[1,1]
	v_pk_mul_f32 v[180:181], v[180:181], v[212:213] op_sel:[0,1] op_sel_hi:[1,1]
	v_pk_fma_f32 v[178:179], v[240:241], v[178:179], v[244:245]
	v_pk_fma_f32 v[180:181], v[242:243], v[180:181], v[246:247]
	v_pk_fma_f32 v[20:21], v[178:179], s[82:83], v[20:21] op_sel_hi:[1,0,1]
	v_pk_fma_f32 v[22:23], v[180:181], s[82:83], v[22:23] op_sel_hi:[1,0,1]
	s_nop 0
	global_store_dwordx4 v126, v[20:23], s[60:61] offset:576 sc1
	global_load_dwordx4 v[178:181], v128, s[60:61] offset:576
	s_waitcnt vmcnt(6)
	v_pk_add_f32 v[182:183], v[182:183], v[214:215] op_sel_hi:[1,0] neg_lo:[0,1] neg_hi:[0,1]
	v_pk_add_f32 v[184:185], v[184:185], v[214:215] op_sel_hi:[1,0] neg_lo:[0,1] neg_hi:[0,1]
	v_pk_mul_f32 v[182:183], v[182:183], v[214:215] op_sel:[0,1] op_sel_hi:[1,1]
	v_pk_mul_f32 v[184:185], v[184:185], v[214:215] op_sel:[0,1] op_sel_hi:[1,1]
	v_pk_fma_f32 v[182:183], v[232:233], v[182:183], v[236:237]
	v_pk_fma_f32 v[184:185], v[234:235], v[184:185], v[238:239]
	v_pk_fma_f32 v[48:49], v[182:183], s[82:83], v[48:49] op_sel_hi:[1,0,1]
	v_pk_fma_f32 v[50:51], v[184:185], s[82:83], v[50:51] op_sel_hi:[1,0,1]
	s_nop 0
	global_store_dwordx4 v127, v[48:51], s[60:61] offset:512 sc1
	global_load_dwordx4 v[182:185], v129, s[60:61] offset:512
	s_waitcnt vmcnt(6)
	v_pk_add_f32 v[186:187], v[186:187], v[214:215] op_sel_hi:[1,0] neg_lo:[0,1] neg_hi:[0,1]
	v_pk_add_f32 v[188:189], v[188:189], v[214:215] op_sel_hi:[1,0] neg_lo:[0,1] neg_hi:[0,1]
	v_pk_mul_f32 v[186:187], v[186:187], v[214:215] op_sel:[0,1] op_sel_hi:[1,1]
	v_pk_mul_f32 v[188:189], v[188:189], v[214:215] op_sel:[0,1] op_sel_hi:[1,1]
	v_pk_fma_f32 v[186:187], v[240:241], v[186:187], v[244:245]
	v_pk_fma_f32 v[188:189], v[242:243], v[188:189], v[246:247]
	v_pk_fma_f32 v[16:17], v[186:187], s[82:83], v[16:17] op_sel_hi:[1,0,1]
	v_pk_fma_f32 v[18:19], v[188:189], s[82:83], v[18:19] op_sel_hi:[1,0,1]
	s_nop 0
	global_store_dwordx4 v127, v[16:19], s[60:61] offset:576 sc1
	global_load_dwordx4 v[186:189], v129, s[60:61] offset:576
	s_waitcnt vmcnt(6)
	v_pk_add_f32 v[174:175], v[174:175], v[216:217] op_sel_hi:[1,0] neg_lo:[0,1] neg_hi:[0,1]
	v_pk_add_f32 v[176:177], v[176:177], v[216:217] op_sel_hi:[1,0] neg_lo:[0,1] neg_hi:[0,1]
	v_pk_mul_f32 v[174:175], v[174:175], v[216:217] op_sel:[0,1] op_sel_hi:[1,1]
	v_pk_mul_f32 v[176:177], v[176:177], v[216:217] op_sel:[0,1] op_sel_hi:[1,1]
	v_pk_fma_f32 v[174:175], v[232:233], v[174:175], v[236:237]
	v_pk_fma_f32 v[176:177], v[234:235], v[176:177], v[238:239]
	v_pk_fma_f32 v[44:45], v[174:175], s[82:83], v[44:45] op_sel_hi:[1,0,1]
	v_pk_fma_f32 v[46:47], v[176:177], s[82:83], v[46:47] op_sel_hi:[1,0,1]
	s_nop 0
	global_store_dwordx4 v128, v[44:47], s[60:61] offset:512 sc1
	global_load_dwordx4 v[174:177], v130, s[60:61] offset:512
	s_waitcnt vmcnt(6)
	v_pk_add_f32 v[178:179], v[178:179], v[216:217] op_sel_hi:[1,0] neg_lo:[0,1] neg_hi:[0,1]
	v_pk_add_f32 v[180:181], v[180:181], v[216:217] op_sel_hi:[1,0] neg_lo:[0,1] neg_hi:[0,1]
	v_pk_mul_f32 v[178:179], v[178:179], v[216:217] op_sel:[0,1] op_sel_hi:[1,1]
	v_pk_mul_f32 v[180:181], v[180:181], v[216:217] op_sel:[0,1] op_sel_hi:[1,1]
	v_pk_fma_f32 v[178:179], v[240:241], v[178:179], v[244:245]
	v_pk_fma_f32 v[180:181], v[242:243], v[180:181], v[246:247]
	v_pk_fma_f32 v[12:13], v[178:179], s[82:83], v[12:13] op_sel_hi:[1,0,1]
	v_pk_fma_f32 v[14:15], v[180:181], s[82:83], v[14:15] op_sel_hi:[1,0,1]
	s_nop 0
	global_store_dwordx4 v128, v[12:15], s[60:61] offset:576 sc1
	global_load_dwordx4 v[178:181], v130, s[60:61] offset:576
	s_waitcnt vmcnt(6)
	v_pk_add_f32 v[182:183], v[182:183], v[218:219] op_sel_hi:[1,0] neg_lo:[0,1] neg_hi:[0,1]
	v_pk_add_f32 v[184:185], v[184:185], v[218:219] op_sel_hi:[1,0] neg_lo:[0,1] neg_hi:[0,1]
	v_pk_mul_f32 v[182:183], v[182:183], v[218:219] op_sel:[0,1] op_sel_hi:[1,1]
	v_pk_mul_f32 v[184:185], v[184:185], v[218:219] op_sel:[0,1] op_sel_hi:[1,1]
	v_pk_fma_f32 v[182:183], v[232:233], v[182:183], v[236:237]
	v_pk_fma_f32 v[184:185], v[234:235], v[184:185], v[238:239]
	v_pk_fma_f32 v[40:41], v[182:183], s[82:83], v[40:41] op_sel_hi:[1,0,1]
	v_pk_fma_f32 v[42:43], v[184:185], s[82:83], v[42:43] op_sel_hi:[1,0,1]
	s_nop 0
	global_store_dwordx4 v129, v[40:43], s[60:61] offset:512 sc1
	global_load_dwordx4 v[182:185], v131, s[60:61] offset:512
	s_waitcnt vmcnt(6)
	v_pk_add_f32 v[186:187], v[186:187], v[218:219] op_sel_hi:[1,0] neg_lo:[0,1] neg_hi:[0,1]
	v_pk_add_f32 v[188:189], v[188:189], v[218:219] op_sel_hi:[1,0] neg_lo:[0,1] neg_hi:[0,1]
	v_pk_mul_f32 v[186:187], v[186:187], v[218:219] op_sel:[0,1] op_sel_hi:[1,1]
	v_pk_mul_f32 v[188:189], v[188:189], v[218:219] op_sel:[0,1] op_sel_hi:[1,1]
	v_pk_fma_f32 v[186:187], v[240:241], v[186:187], v[244:245]
	v_pk_fma_f32 v[188:189], v[242:243], v[188:189], v[246:247]
	v_pk_fma_f32 v[8:9], v[186:187], s[82:83], v[8:9] op_sel_hi:[1,0,1]
	v_pk_fma_f32 v[10:11], v[188:189], s[82:83], v[10:11] op_sel_hi:[1,0,1]
	s_nop 0
	global_store_dwordx4 v129, v[8:11], s[60:61] offset:576 sc1
	global_load_dwordx4 v[186:189], v131, s[60:61] offset:576
	s_waitcnt vmcnt(6)
	v_pk_add_f32 v[174:175], v[174:175], v[220:221] op_sel_hi:[1,0] neg_lo:[0,1] neg_hi:[0,1]
	v_pk_add_f32 v[176:177], v[176:177], v[220:221] op_sel_hi:[1,0] neg_lo:[0,1] neg_hi:[0,1]
	v_pk_mul_f32 v[174:175], v[174:175], v[220:221] op_sel:[0,1] op_sel_hi:[1,1]
	v_pk_mul_f32 v[176:177], v[176:177], v[220:221] op_sel:[0,1] op_sel_hi:[1,1]
	v_pk_fma_f32 v[174:175], v[232:233], v[174:175], v[236:237]
	v_pk_fma_f32 v[176:177], v[234:235], v[176:177], v[238:239]
	v_pk_fma_f32 v[36:37], v[174:175], s[82:83], v[36:37] op_sel_hi:[1,0,1]
	v_pk_fma_f32 v[38:39], v[176:177], s[82:83], v[38:39] op_sel_hi:[1,0,1]
	s_nop 0
	global_store_dwordx4 v130, v[36:39], s[60:61] offset:512 sc1
	s_waitcnt vmcnt(5)
	v_pk_add_f32 v[178:179], v[178:179], v[220:221] op_sel_hi:[1,0] neg_lo:[0,1] neg_hi:[0,1]
	v_pk_add_f32 v[180:181], v[180:181], v[220:221] op_sel_hi:[1,0] neg_lo:[0,1] neg_hi:[0,1]
	v_pk_mul_f32 v[178:179], v[178:179], v[220:221] op_sel:[0,1] op_sel_hi:[1,1]
	v_pk_mul_f32 v[180:181], v[180:181], v[220:221] op_sel:[0,1] op_sel_hi:[1,1]
	v_pk_fma_f32 v[178:179], v[240:241], v[178:179], v[244:245]
	v_pk_fma_f32 v[180:181], v[242:243], v[180:181], v[246:247]
	v_pk_fma_f32 v[4:5], v[178:179], s[82:83], v[4:5] op_sel_hi:[1,0,1]
	v_pk_fma_f32 v[6:7], v[180:181], s[82:83], v[6:7] op_sel_hi:[1,0,1]
	s_nop 0
	global_store_dwordx4 v130, v[4:7], s[60:61] offset:576 sc1
	s_waitcnt vmcnt(4)
	v_pk_add_f32 v[182:183], v[182:183], v[230:231] op_sel_hi:[1,0] neg_lo:[0,1] neg_hi:[0,1]
	v_pk_add_f32 v[184:185], v[184:185], v[230:231] op_sel_hi:[1,0] neg_lo:[0,1] neg_hi:[0,1]
	v_pk_mul_f32 v[182:183], v[182:183], v[230:231] op_sel:[0,1] op_sel_hi:[1,1]
	v_pk_mul_f32 v[184:185], v[184:185], v[230:231] op_sel:[0,1] op_sel_hi:[1,1]
	v_pk_fma_f32 v[182:183], v[232:233], v[182:183], v[236:237]
	v_pk_fma_f32 v[184:185], v[234:235], v[184:185], v[238:239]
	v_pk_fma_f32 v[28:29], v[182:183], s[82:83], v[28:29] op_sel_hi:[1,0,1]
	v_pk_fma_f32 v[30:31], v[184:185], s[82:83], v[30:31] op_sel_hi:[1,0,1]
	s_nop 0
	global_store_dwordx4 v131, v[28:31], s[60:61] offset:512 sc1
	s_waitcnt vmcnt(3)
	v_pk_add_f32 v[186:187], v[186:187], v[230:231] op_sel_hi:[1,0] neg_lo:[0,1] neg_hi:[0,1]
	v_pk_add_f32 v[188:189], v[188:189], v[230:231] op_sel_hi:[1,0] neg_lo:[0,1] neg_hi:[0,1]
	v_pk_mul_f32 v[186:187], v[186:187], v[230:231] op_sel:[0,1] op_sel_hi:[1,1]
	v_pk_mul_f32 v[188:189], v[188:189], v[230:231] op_sel:[0,1] op_sel_hi:[1,1]
	v_pk_fma_f32 v[186:187], v[240:241], v[186:187], v[244:245]
	v_pk_fma_f32 v[188:189], v[242:243], v[188:189], v[246:247]
	v_pk_fma_f32 v[0:1], v[186:187], s[82:83], v[0:1] op_sel_hi:[1,0,1]
	v_pk_fma_f32 v[2:3], v[188:189], s[82:83], v[2:3] op_sel_hi:[1,0,1]
	s_nop 0
	global_store_dwordx4 v131, v[0:3], s[60:61] offset:576 sc1
	s_nop 3
	s_mov_b64 s[60:61], -1
	s_andn2_b64 vcc, exec, s[36:37]
	s_cbranch_vccnz .LBB0_1075
	s_andn2_b64 vcc, exec, s[48:49]
	s_cbranch_vccnz .LBB0_1074
	s_barrier
	s_branch .LBB0_1074
